# EpiProj epilogues: rope-table loads issued before the next-tile DMA prefetch, epilogue waits with vmcnt(8) so the prefetch stays in flight
# baseline (speedup 1.0000x reference)
; __device__ __forceinline__ f32x4 mfma16(bf16x8 a, bf16x8 b, f32x4 c) { return __builtin_amdgcn_mfma_f32_16x16x32_bf16(a, b, c, 0, 0, 0); }
; template <class Epi>
; __device__ __forceinline__ void gemm_tile(const bf16_t* __restrict__ A, const bf16_t* __restrict__ Bt, int K, int row0, int col0, const Epi& epi, char* smem,
;                                           bool prefetched, bool nvalid, int nrow0, int ncol0) {
;     ...
;     for (int kt = 0; kt < nk; ++kt) {
;         const int cur = kt & 1;
;         if (kt + 1 < nk) GLDS_STAGE(cur ^ 1, pA, pB, kt + 1);
;         const char* cb = smem + cur * 2 * TILE_B;
; #pragma unroll
;         for (int ks = 0; ks < 2; ++ks) {
;             bf16x8 a[4], b[4];
; #pragma unroll
;             for (int m = 0; m < 4; ++m) a[m] = *(const bf16x8*)(cb + offA[m][ks]);
; #pragma unroll
;             for (int n = 0; n < 4; ++n) b[n] = *(const bf16x8*)(cb + offB[n][ks]);
; #pragma unroll
;             for (int m = 0; m < 4; ++m)
; #pragma unroll
;                 for (int n = 0; n < 4; ++n) acc[m][n] = mfma16(b[n], a[m], acc[m][n]);
;         }
;         asm volatile("s_waitcnt vmcnt(0)" ::: "memory");
;         __syncthreads();
;     }
;     if (nvalid) { const bf16_t* qA = A + (size_t)nrow0 * K; const bf16_t* qB = Bt + (size_t)ncol0 * K; GLDS_STAGE(0, qA, qB, 0); }
;     __device__ __forceinline__ void to_lds(f32x4 (&acc)[4][4], bf16_t* st, int row0, int col0, int wr, int wc, int fr, int fq) const {
;     ...
;                     const float* rp = rope + s * 16;
;                     const f32x4 c0 = *(const f32x4*)rp, c1 = *(const f32x4*)(rp + 4), s0 = *(const f32x4*)(rp + 8), s1 = *(const f32x4*)(rp + 12);
.Lgk_tail_154:
	s_setprio 0
	v_mfma_f32_16x16x32_bf16 v[32:35], v[80:83], v[246:249], v[32:35]
	v_mfma_f32_16x16x32_bf16 v[36:39], v[128:131], v[246:249], v[36:39]
	v_mfma_f32_16x16x32_bf16 v[40:43], v[174:177], v[246:249], v[40:43]
	v_mfma_f32_16x16x32_bf16 v[44:47], v[178:181], v[246:249], v[44:47]
	v_mfma_f32_16x16x32_bf16 v[48:51], v[80:83], v[250:253], v[48:51]
	v_mfma_f32_16x16x32_bf16 v[52:55], v[128:131], v[250:253], v[52:55]
	v_mfma_f32_16x16x32_bf16 v[56:59], v[174:177], v[250:253], v[56:59]
	v_mfma_f32_16x16x32_bf16 v[60:63], v[178:181], v[250:253], v[60:63]
	ds_read_b128 v[64:67], v142 offset:49152
	ds_read_b128 v[68:71], v139 offset:32768
	ds_read_b128 v[72:75], v142 offset:49664
	ds_read_b128 v[76:79], v142 offset:53248
	ds_read_b128 v[80:83], v142 offset:53760
	s_add_i32 s21, s21, s58
	s_waitcnt lgkmcnt(3)
	v_mfma_f32_16x16x32_bf16 v[0:3], v[64:67], v[68:71], v[0:3]
	s_cmpk_gt_i32 s21, 0x10ff
	s_cselect_b64 s[8:9], -1, 0
	s_cmpk_lt_i32 s21, 0x1100
	s_waitcnt lgkmcnt(2)
	v_mfma_f32_16x16x32_bf16 v[4:7], v[72:75], v[68:71], v[4:7]
	ds_read_b128 v[182:185], v141 offset:49152
	ds_read_b128 v[186:189], v141 offset:53760
	s_waitcnt lgkmcnt(3)
	v_mfma_f32_16x16x32_bf16 v[8:11], v[76:79], v[68:71], v[8:11]
	s_waitcnt lgkmcnt(2)
	v_mfma_f32_16x16x32_bf16 v[12:15], v[80:83], v[68:71], v[12:15]
	ds_read_b128 v[68:71], v139 offset:34816
	s_waitcnt lgkmcnt(0)
	v_mfma_f32_16x16x32_bf16 v[16:19], v[64:67], v[68:71], v[16:19]
	v_mfma_f32_16x16x32_bf16 v[20:23], v[72:75], v[68:71], v[20:23]
	v_mfma_f32_16x16x32_bf16 v[24:27], v[76:79], v[68:71], v[24:27]
	v_mfma_f32_16x16x32_bf16 v[28:31], v[80:83], v[68:71], v[28:31]
	ds_read_b128 v[68:71], v139 offset:36864
	s_waitcnt lgkmcnt(0)
	v_mfma_f32_16x16x32_bf16 v[128:131], v[64:67], v[68:71], v[32:35]
	s_nop 2
	ds_read_b128 v[32:35], v139 offset:38912
	v_mfma_f32_16x16x32_bf16 v[174:177], v[72:75], v[68:71], v[36:39]
	v_mfma_f32_16x16x32_bf16 v[178:181], v[76:79], v[68:71], v[40:43]
	v_mfma_f32_16x16x32_bf16 v[68:71], v[80:83], v[68:71], v[44:47]
	s_waitcnt lgkmcnt(0)
	v_mfma_f32_16x16x32_bf16 v[64:67], v[64:67], v[32:35], v[48:51]
	v_mfma_f32_16x16x32_bf16 v[72:75], v[72:75], v[32:35], v[52:55]
	v_mfma_f32_16x16x32_bf16 v[76:79], v[76:79], v[32:35], v[56:59]
	v_mfma_f32_16x16x32_bf16 v[80:83], v[80:83], v[32:35], v[60:63]
	ds_read_b128 v[32:35], v140 offset:32768
	s_waitcnt lgkmcnt(0)
	v_mfma_f32_16x16x32_bf16 v[56:59], v[182:185], v[32:35], v[0:3]
	s_nop 2
	ds_read_b128 v[0:3], v141 offset:49664
	s_waitcnt lgkmcnt(0)
	v_mfma_f32_16x16x32_bf16 v[60:63], v[0:3], v[32:35], v[4:7]
	s_nop 2
	ds_read_b128 v[4:7], v141 offset:53248
	s_waitcnt lgkmcnt(0)
	v_mfma_f32_16x16x32_bf16 v[48:51], v[4:7], v[32:35], v[8:11]
	s_nop 2
	ds_read_b128 v[8:11], v140 offset:34816
	v_mfma_f32_16x16x32_bf16 v[52:55], v[186:189], v[32:35], v[12:15]
	s_waitcnt lgkmcnt(0)
	v_mfma_f32_16x16x32_bf16 v[40:43], v[182:185], v[8:11], v[16:19]
	v_mfma_f32_16x16x32_bf16 v[44:47], v[0:3], v[8:11], v[20:23]
	v_mfma_f32_16x16x32_bf16 v[32:35], v[4:7], v[8:11], v[24:27]
	v_mfma_f32_16x16x32_bf16 v[36:39], v[186:189], v[8:11], v[28:31]
	ds_read_b128 v[8:11], v140 offset:36864
	s_waitcnt lgkmcnt(0)
	v_mfma_f32_16x16x32_bf16 v[20:23], v[186:189], v[8:11], v[68:71]
	s_nop 2
	ds_read_b128 v[68:71], v140 offset:38912
	s_waitcnt vmcnt(0)
	v_mfma_f32_16x16x32_bf16 v[24:27], v[182:185], v[8:11], v[128:131]
	s_waitcnt lgkmcnt(0)
	s_barrier
	v_mfma_f32_16x16x32_bf16 v[28:31], v[0:3], v[8:11], v[174:177]
	v_mfma_f32_16x16x32_bf16 v[16:19], v[4:7], v[8:11], v[178:181]
	v_mfma_f32_16x16x32_bf16 v[8:11], v[182:185], v[68:71], v[64:67]
	v_mfma_f32_16x16x32_bf16 v[12:15], v[0:3], v[68:71], v[72:75]
	v_mfma_f32_16x16x32_bf16 v[0:3], v[4:7], v[68:71], v[76:79]
	v_mfma_f32_16x16x32_bf16 v[4:7], v[186:189], v[68:71], v[80:83]
	v_readlane_b32 s100, v245, 47
	v_readlane_b32 s101, v245, 48
	v_add_lshl_u32 v255, s4, v117, 6
	v_and_b32_e32 v255, 0x3f3c0, v255
	s_nop 4
	global_load_dwordx4 v[180:183], v255, s[100:101] offset:48
	global_load_dwordx4 v[184:187], v255, s[100:101] offset:32
	global_load_dwordx4 v[188:191], v255, s[100:101] offset:16
	global_load_dwordx4 v[192:195], v255, s[100:101]
	v_add_lshl_u32 v254, s4, v143, 6
	v_and_b32_e32 v254, 0x3f7c0, v254
	global_load_dwordx4 v[196:199], v254, s[100:101] offset:48
	global_load_dwordx4 v[200:203], v254, s[100:101] offset:32
	global_load_dwordx4 v[204:207], v254, s[100:101] offset:16
	global_load_dwordx4 v[208:211], v254, s[100:101]
	v_add_lshl_u32 v255, s4, v144, 6
	v_and_b32_e32 v255, 0x3fbc0, v255
	global_load_dwordx4 v[212:215], v255, s[100:101] offset:48
	global_load_dwordx4 v[216:219], v255, s[100:101] offset:32
	global_load_dwordx4 v[220:223], v255, s[100:101] offset:16
	global_load_dwordx4 v[224:227], v255, s[100:101]
	v_add_lshl_u32 v254, s4, v145, 6
	v_and_b32_e32 v254, 0x3ffc0, v254
	global_load_dwordx4 v[228:231], v254, s[100:101] offset:48
	global_load_dwordx4 v[232:235], v254, s[100:101] offset:32
	global_load_dwordx4 v[236:239], v254, s[100:101] offset:16
	global_load_dwordx4 v[240:243], v254, s[100:101]
	s_cbranch_scc0 .Lnp_154
	s_mul_hi_i32 s0, s21, 0x78787879
	s_lshr_b32 s1, s0, 31
	s_ashr_i32 s0, s0, 3
	s_add_i32 s1, s0, s1
	s_lshl_b32 s0, s1, 7
	s_mul_i32 s1, s1, 17
	s_sub_i32 s1, s21, s1
	s_lshl_b32 s10, s1, 7
	s_ashr_i32 s1, s0, 31
	s_lshl_b64 s[0:1], s[0:1], 11
	v_readlane_b32 s5, v245, 53
	s_add_u32 s0, s5, s0
	v_readlane_b32 s5, v245, 54
	s_addc_u32 s1, s5, s1
	s_ashr_i32 s11, s10, 31
	s_lshl_b64 s[10:11], s[10:11], 11
	s_add_u32 s10, s56, s10
	v_readfirstlane_b32 s5, v149
	s_addc_u32 s11, s57, s11
	s_mov_b32 m0, s5
	v_readfirstlane_b32 s5, v159
	global_load_lds_dwordx4 v167, s[0:1]
	v_lshl_add_u64 v[64:65], v[84:85], 1, s[10:11]
	s_mov_b32 m0, s5
	v_readfirstlane_b32 s5, v160
	global_load_lds_dwordx4 v[64:65], off
	s_mov_b32 m0, s5
	v_readfirstlane_b32 s5, v161
	global_load_lds_dwordx4 v168, s[0:1]
	v_lshl_add_u64 v[64:65], v[86:87], 1, s[10:11]
	s_mov_b32 m0, s5
	v_readfirstlane_b32 s5, v162
	global_load_lds_dwordx4 v[64:65], off
	s_mov_b32 m0, s5
	v_readfirstlane_b32 s5, v163
	global_load_lds_dwordx4 v169, s[0:1]
	v_lshl_add_u64 v[64:65], v[88:89], 1, s[10:11]
	s_mov_b32 m0, s5
	v_readfirstlane_b32 s5, v164
	global_load_lds_dwordx4 v[64:65], off
	s_mov_b32 m0, s5
	v_lshl_add_u64 v[64:65], v[90:91], 1, s[10:11]
	global_load_lds_dwordx4 v170, s[0:1]
	v_readfirstlane_b32 s0, v165
	s_mov_b32 m0, s0
	s_nop 0
	global_load_lds_dwordx4 v[64:65], off
	s_branch .LBB0_157
;     __device__ __forceinline__ void to_lds(f32x4 (&acc)[4][4], bf16_t* st, int row0, int col0, int wr, int wc, int fr, int fq) const {
;     ...
;                 if (pp == 0 && dorope) {
;                     f32x4 p0, p1;
; #pragma unroll
;                     for (int j = 0; j < 4; ++j) { p0[j] = __shfl_xor(v0[j], 16); p1[j] = __shfl_xor(v1[j], 16); }
;                     const float* rp = rope + s * 16;
;                     const f32x4 c0 = *(const f32x4*)rp, c1 = *(const f32x4*)(rp + 4), s0 = *(const f32x4*)(rp + 8), s1 = *(const f32x4*)(rp + 12);
;                     if (fq == 0) { v0 = v0 * c0 - p0 * s0; v1 = v1 * c1 - p1 * s1; }
;                     else if (fq == 1) { v0 = v0 * c0 + p0 * s0; v1 = v1 * c1 + p1 * s1; }
;                 }
.Lnp_154:
	v_mov_b32_e32 v255, 0
	global_load_dword v246, v255, s[100:101]
	global_load_dword v246, v255, s[100:101]
	global_load_dword v246, v255, s[100:101]
	global_load_dword v246, v255, s[100:101]
	global_load_dword v246, v255, s[100:101]
	global_load_dword v246, v255, s[100:101]
	global_load_dword v246, v255, s[100:101]
	global_load_dword v246, v255, s[100:101]
.LBB0_157:
	v_or_b32_e32 v64, s6, v148
	s_cmpk_lt_u32 s6, 0x800
	s_cselect_b64 s[10:11], -1, 0
	v_cmp_lt_i32_e64 s[0:1], s19, v64
	v_cmp_gt_i32_e32 vcc, s18, v64
	s_and_b64 s[0:1], s[10:11], s[0:1]
	s_or_b64 s[10:11], vcc, s[0:1]
	s_and_saveexec_b64 s[12:13], s[10:11]
	s_cbranch_execz .LBB0_165
	v_and_b32_e32 v65, 64, v171
	v_xor_b32_e32 v64, 16, v171
	v_add_u32_e32 v65, 64, v65
	v_cmp_lt_i32_e64 s[0:1], v64, v65
	s_nop 1
	v_cndmask_b32_e64 v64, v171, v64, s[0:1]
	v_lshlrev_b32_e32 v66, 2, v64
	ds_bpermute_b32 v74, v66, v56
	ds_bpermute_b32 v64, v66, v60
	ds_bpermute_b32 v75, v66, v57
	ds_bpermute_b32 v65, v66, v61
	ds_bpermute_b32 v130, v66, v58
	ds_bpermute_b32 v128, v66, v62
	ds_bpermute_b32 v131, v66, v59
	ds_bpermute_b32 v129, v66, v63
	v_add_lshl_u32 v66, s4, v117, 6
	v_readlane_b32 s0, v245, 47
	v_and_b32_e32 v76, 0x3f3c0, v66
	v_readlane_b32 s1, v245, 48
	s_nop 4
	s_waitcnt vmcnt(8)
	v_mov_b32_e32 v70, v180
	v_mov_b32_e32 v71, v181
	v_mov_b32_e32 v72, v182
	v_mov_b32_e32 v73, v183
	v_mov_b32_e32 v80, v184
	v_mov_b32_e32 v81, v185
	v_mov_b32_e32 v82, v186
	v_mov_b32_e32 v83, v187
	v_mov_b32_e32 v66, v188
	v_mov_b32_e32 v67, v189
	v_mov_b32_e32 v68, v190
	v_mov_b32_e32 v69, v191
	s_nop 0
	v_mov_b32_e32 v76, v192
	v_mov_b32_e32 v77, v193
	v_mov_b32_e32 v78, v194
	v_mov_b32_e32 v79, v195
	v_cmp_lt_i32_e64 s[0:1], 0, v133
	s_and_saveexec_b64 s[14:15], s[0:1]
	s_xor_b64 s[14:15], exec, s[14:15]
	s_cbranch_execz .LBB0_162
	v_cmp_eq_u32_e64 s[0:1], 1, v133
	s_and_saveexec_b64 s[16:17], s[0:1]
	s_cbranch_execz .LBB0_161
	s_waitcnt vmcnt(8) lgkmcnt(0)
	v_pk_mul_f32 v[82:83], v[82:83], v[130:131]
	v_pk_mul_f32 v[74:75], v[80:81], v[74:75]
	v_pk_mul_f32 v[72:73], v[72:73], v[128:129]
	v_pk_mul_f32 v[64:65], v[70:71], v[64:65]
	v_pk_fma_f32 v[58:59], v[58:59], v[78:79], v[82:83]
	v_pk_fma_f32 v[56:57], v[56:57], v[76:77], v[74:75]
	v_pk_fma_f32 v[62:63], v[62:63], v[68:69], v[72:73]
	v_pk_fma_f32 v[60:61], v[60:61], v[66:67], v[64:65]

;     __device__ __forceinline__ void to_lds(f32x4 (&acc)[4][4], bf16_t* st, int row0, int col0, int wr, int wc, int fr, int fq) const {
;     ...
;                 if (pp == 0 && dorope) {
;                     f32x4 p0, p1;
; #pragma unroll
;                     for (int j = 0; j < 4; ++j) { p0[j] = __shfl_xor(v0[j], 16); p1[j] = __shfl_xor(v1[j], 16); }
;                     const float* rp = rope + s * 16;
;                     const f32x4 c0 = *(const f32x4*)rp, c1 = *(const f32x4*)(rp + 4), s0 = *(const f32x4*)(rp + 8), s1 = *(const f32x4*)(rp + 12);
;                     if (fq == 0) { v0 = v0 * c0 - p0 * s0; v1 = v1 * c1 - p1 * s1; }
;                     else if (fq == 1) { v0 = v0 * c0 + p0 * s0; v1 = v1 * c1 + p1 * s1; }
;                 }
.LBB0_162:
	s_andn2_saveexec_b64 s[0:1], s[14:15]
	s_cbranch_execz .LBB0_164
	s_waitcnt vmcnt(8) lgkmcnt(0)
	v_pk_mul_f32 v[82:83], v[82:83], v[130:131]
	v_pk_mul_f32 v[74:75], v[80:81], v[74:75]
	v_pk_mul_f32 v[72:73], v[72:73], v[128:129]
	v_pk_mul_f32 v[64:65], v[70:71], v[64:65]
	v_pk_fma_f32 v[58:59], v[58:59], v[78:79], v[82:83] neg_lo:[0,0,1] neg_hi:[0,0,1]
	v_pk_fma_f32 v[56:57], v[56:57], v[76:77], v[74:75] neg_lo:[0,0,1] neg_hi:[0,0,1]
	v_pk_fma_f32 v[62:63], v[62:63], v[68:69], v[72:73] neg_lo:[0,0,1] neg_hi:[0,0,1]
	v_pk_fma_f32 v[60:61], v[60:61], v[66:67], v[64:65] neg_lo:[0,0,1] neg_hi:[0,0,1]

; __device__ __forceinline__ u32x4 pack8(f32x4 a, f32x4 b) { u32x4 r; r.x = cvt_pk_bf16(a[0], a[1]); r.y = cvt_pk_bf16(a[2], a[3]); r.z = cvt_pk_bf16(b[0], b[1]); r.w = cvt_pk_bf16(b[2], b[3]); return r; }
;     __device__ __forceinline__ void to_lds(f32x4 (&acc)[4][4], bf16_t* st, int row0, int col0, int wr, int wc, int fr, int fq) const {
;     ...
;             for (int pp = 0; pp < 2; ++pp) {
;                 f32x4 v0 = acc[m][2 * pp], v1 = acc[m][2 * pp + 1];
;                 if (pp == 0 && dorope) {
;                     f32x4 p0, p1;
; #pragma unroll
;                     for (int j = 0; j < 4; ++j) { p0[j] = __shfl_xor(v0[j], 16); p1[j] = __shfl_xor(v1[j], 16); }
;                     const float* rp = rope + s * 16;
;                     const f32x4 c0 = *(const f32x4*)rp, c1 = *(const f32x4*)(rp + 4), s0 = *(const f32x4*)(rp + 8), s1 = *(const f32x4*)(rp + 12);
;                     if (fq == 0) { v0 = v0 * c0 - p0 * s0; v1 = v1 * c1 - p1 * s1; }
;                     else if (fq == 1) { v0 = v0 * c0 + p0 * s0; v1 = v1 * c1 + p1 * s1; }
;                 }
;                 if (isq) { v0 = v0 * 0.18033688011112042f; v1 = v1 * 0.18033688011112042f; }
;                 *(u32x4*)(st + rl * 136 + wc * 64 + pp * 32 + 8 * fq) = pack8(v0, v1);
.LBB0_165:
	s_or_b64 exec, exec, s[12:13]
	s_waitcnt lgkmcnt(0)
	v_pk_mul_f32 v[64:65], v[58:59], s[2:3] op_sel_hi:[1,0]
	s_waitcnt vmcnt(8)
	v_pk_mul_f32 v[66:67], v[56:57], s[2:3] op_sel_hi:[1,0]
	v_pk_mul_f32 v[68:69], v[62:63], s[2:3] op_sel_hi:[1,0]
	v_pk_mul_f32 v[70:71], v[60:61], s[2:3] op_sel_hi:[1,0]
	v_cndmask_b32_e32 v63, v63, v69, vcc
	v_cndmask_b32_e32 v62, v62, v68, vcc
	v_cndmask_b32_e32 v61, v61, v71, vcc
	v_cndmask_b32_e32 v60, v60, v70, vcc
	v_cndmask_b32_e32 v59, v59, v65, vcc
	v_cndmask_b32_e32 v58, v58, v64, vcc
	v_cndmask_b32_e32 v57, v57, v67, vcc
	v_cndmask_b32_e32 v56, v56, v66, vcc
	v_cvt_pk_bf16_f32 v56, v56, v57
	v_cvt_pk_bf16_f32 v57, v58, v59
	v_cvt_pk_bf16_f32 v58, v60, v61
	v_cvt_pk_bf16_f32 v59, v62, v63
	ds_write_b128 v172, v[56:59] offset:32768
	v_pk_mul_f32 v[56:57], v[50:51], s[2:3] op_sel_hi:[1,0]
	v_pk_mul_f32 v[58:59], v[48:49], s[2:3] op_sel_hi:[1,0]
	v_pk_mul_f32 v[60:61], v[54:55], s[2:3] op_sel_hi:[1,0]
	v_pk_mul_f32 v[62:63], v[52:53], s[2:3] op_sel_hi:[1,0]
	v_cndmask_b32_e32 v55, v55, v61, vcc
	v_cndmask_b32_e32 v54, v54, v60, vcc
	v_cndmask_b32_e32 v53, v53, v63, vcc
	v_cndmask_b32_e32 v52, v52, v62, vcc
	v_cndmask_b32_e32 v51, v51, v57, vcc
	v_cndmask_b32_e32 v50, v50, v56, vcc
	v_cndmask_b32_e32 v49, v49, v59, vcc
	v_cndmask_b32_e32 v48, v48, v58, vcc
	v_cvt_pk_bf16_f32 v48, v48, v49
	v_cvt_pk_bf16_f32 v49, v50, v51
	v_cvt_pk_bf16_f32 v50, v52, v53
	v_cvt_pk_bf16_f32 v51, v54, v55
	ds_write_b128 v172, v[48:51] offset:32832
	s_and_saveexec_b64 s[12:13], s[10:11]
	s_cbranch_execz .LBB0_173
	v_and_b32_e32 v49, 64, v171
	v_xor_b32_e32 v48, 16, v171
	v_add_u32_e32 v49, 64, v49
	v_cmp_lt_i32_e64 s[0:1], v48, v49
	s_nop 1
	v_cndmask_b32_e64 v48, v171, v48, s[0:1]
	v_lshlrev_b32_e32 v50, 2, v48
	ds_bpermute_b32 v58, v50, v40
	ds_bpermute_b32 v48, v50, v44
	ds_bpermute_b32 v59, v50, v41
	ds_bpermute_b32 v49, v50, v45
	ds_bpermute_b32 v70, v50, v42
	ds_bpermute_b32 v68, v50, v46
	ds_bpermute_b32 v71, v50, v43
	ds_bpermute_b32 v69, v50, v47
	v_add_lshl_u32 v50, s4, v143, 6
	v_readlane_b32 s0, v245, 47
	v_and_b32_e32 v60, 0x3f7c0, v50
	v_readlane_b32 s1, v245, 48
	s_nop 4
	v_mov_b32_e32 v54, v196
	v_mov_b32_e32 v55, v197
	v_mov_b32_e32 v56, v198
	v_mov_b32_e32 v57, v199
	v_mov_b32_e32 v64, v200
	v_mov_b32_e32 v65, v201
	v_mov_b32_e32 v66, v202
	v_mov_b32_e32 v67, v203
	v_mov_b32_e32 v50, v204
	v_mov_b32_e32 v51, v205
	v_mov_b32_e32 v52, v206
	v_mov_b32_e32 v53, v207
	s_nop 0
	v_mov_b32_e32 v60, v208
	v_mov_b32_e32 v61, v209
	v_mov_b32_e32 v62, v210
	v_mov_b32_e32 v63, v211
	v_cmp_lt_i32_e64 s[0:1], 0, v133
	s_and_saveexec_b64 s[14:15], s[0:1]
	s_xor_b64 s[14:15], exec, s[14:15]
	s_cbranch_execz .LBB0_170
	v_cmp_eq_u32_e64 s[0:1], 1, v133
	s_and_saveexec_b64 s[16:17], s[0:1]
	s_cbranch_execz .LBB0_169
	s_waitcnt vmcnt(8) lgkmcnt(1)
	v_pk_mul_f32 v[66:67], v[66:67], v[70:71]
	v_pk_mul_f32 v[58:59], v[64:65], v[58:59]
	s_waitcnt lgkmcnt(0)
	v_pk_mul_f32 v[56:57], v[56:57], v[68:69]
	v_pk_mul_f32 v[48:49], v[54:55], v[48:49]
	s_waitcnt vmcnt(8)
	v_pk_fma_f32 v[42:43], v[42:43], v[62:63], v[66:67]
	v_pk_fma_f32 v[40:41], v[40:41], v[60:61], v[58:59]
	v_pk_fma_f32 v[46:47], v[46:47], v[52:53], v[56:57]
	v_pk_fma_f32 v[44:45], v[44:45], v[50:51], v[48:49]

;     __device__ __forceinline__ void to_lds(f32x4 (&acc)[4][4], bf16_t* st, int row0, int col0, int wr, int wc, int fr, int fq) const {
;     ...
;                 if (pp == 0 && dorope) {
;                     f32x4 p0, p1;
; #pragma unroll
;                     for (int j = 0; j < 4; ++j) { p0[j] = __shfl_xor(v0[j], 16); p1[j] = __shfl_xor(v1[j], 16); }
;                     const float* rp = rope + s * 16;
;                     const f32x4 c0 = *(const f32x4*)rp, c1 = *(const f32x4*)(rp + 4), s0 = *(const f32x4*)(rp + 8), s1 = *(const f32x4*)(rp + 12);
;                     if (fq == 0) { v0 = v0 * c0 - p0 * s0; v1 = v1 * c1 - p1 * s1; }
;                     else if (fq == 1) { v0 = v0 * c0 + p0 * s0; v1 = v1 * c1 + p1 * s1; }
;                 }
.LBB0_170:
	s_andn2_saveexec_b64 s[0:1], s[14:15]
	s_cbranch_execz .LBB0_172
	s_waitcnt vmcnt(8) lgkmcnt(1)
	v_pk_mul_f32 v[66:67], v[66:67], v[70:71]
	v_pk_mul_f32 v[58:59], v[64:65], v[58:59]
	s_waitcnt lgkmcnt(0)
	v_pk_mul_f32 v[56:57], v[56:57], v[68:69]
	v_pk_mul_f32 v[48:49], v[54:55], v[48:49]
	s_waitcnt vmcnt(8)
	v_pk_fma_f32 v[42:43], v[42:43], v[62:63], v[66:67] neg_lo:[0,0,1] neg_hi:[0,0,1]
	v_pk_fma_f32 v[40:41], v[40:41], v[60:61], v[58:59] neg_lo:[0,0,1] neg_hi:[0,0,1]
	v_pk_fma_f32 v[46:47], v[46:47], v[52:53], v[56:57] neg_lo:[0,0,1] neg_hi:[0,0,1]
	v_pk_fma_f32 v[44:45], v[44:45], v[50:51], v[48:49] neg_lo:[0,0,1] neg_hi:[0,0,1]

; __device__ __forceinline__ u32x4 pack8(f32x4 a, f32x4 b) { u32x4 r; r.x = cvt_pk_bf16(a[0], a[1]); r.y = cvt_pk_bf16(a[2], a[3]); r.z = cvt_pk_bf16(b[0], b[1]); r.w = cvt_pk_bf16(b[2], b[3]); return r; }
;     __device__ __forceinline__ void to_lds(f32x4 (&acc)[4][4], bf16_t* st, int row0, int col0, int wr, int wc, int fr, int fq) const {
;     ...
;             for (int pp = 0; pp < 2; ++pp) {
;                 f32x4 v0 = acc[m][2 * pp], v1 = acc[m][2 * pp + 1];
;                 if (pp == 0 && dorope) {
;                     f32x4 p0, p1;
; #pragma unroll
;                     for (int j = 0; j < 4; ++j) { p0[j] = __shfl_xor(v0[j], 16); p1[j] = __shfl_xor(v1[j], 16); }
;                     const float* rp = rope + s * 16;
;                     const f32x4 c0 = *(const f32x4*)rp, c1 = *(const f32x4*)(rp + 4), s0 = *(const f32x4*)(rp + 8), s1 = *(const f32x4*)(rp + 12);
;                     if (fq == 0) { v0 = v0 * c0 - p0 * s0; v1 = v1 * c1 - p1 * s1; }
;                     else if (fq == 1) { v0 = v0 * c0 + p0 * s0; v1 = v1 * c1 + p1 * s1; }
;                 }
;                 if (isq) { v0 = v0 * 0.18033688011112042f; v1 = v1 * 0.18033688011112042f; }
;                 *(u32x4*)(st + rl * 136 + wc * 64 + pp * 32 + 8 * fq) = pack8(v0, v1);
.LBB0_173:
	s_or_b64 exec, exec, s[12:13]
	s_waitcnt lgkmcnt(4)
	v_pk_mul_f32 v[48:49], v[42:43], s[2:3] op_sel_hi:[1,0]
	s_waitcnt vmcnt(8)
	v_pk_mul_f32 v[50:51], v[40:41], s[2:3] op_sel_hi:[1,0]
	v_pk_mul_f32 v[52:53], v[46:47], s[2:3] op_sel_hi:[1,0]
	v_pk_mul_f32 v[54:55], v[44:45], s[2:3] op_sel_hi:[1,0]
	v_cndmask_b32_e32 v47, v47, v53, vcc
	v_cndmask_b32_e32 v46, v46, v52, vcc
	v_cndmask_b32_e32 v45, v45, v55, vcc
	v_cndmask_b32_e32 v44, v44, v54, vcc
	v_cndmask_b32_e32 v43, v43, v49, vcc
	v_cndmask_b32_e32 v42, v42, v48, vcc
	v_cndmask_b32_e32 v41, v41, v51, vcc
	v_cndmask_b32_e32 v40, v40, v50, vcc
	v_cvt_pk_bf16_f32 v40, v40, v41
	v_cvt_pk_bf16_f32 v41, v42, v43
	v_cvt_pk_bf16_f32 v42, v44, v45
	v_cvt_pk_bf16_f32 v43, v46, v47
	ds_write_b128 v172, v[40:43] offset:37120
	v_pk_mul_f32 v[40:41], v[34:35], s[2:3] op_sel_hi:[1,0]
	v_pk_mul_f32 v[42:43], v[32:33], s[2:3] op_sel_hi:[1,0]
	v_pk_mul_f32 v[44:45], v[38:39], s[2:3] op_sel_hi:[1,0]
	v_pk_mul_f32 v[46:47], v[36:37], s[2:3] op_sel_hi:[1,0]
	v_cndmask_b32_e32 v39, v39, v45, vcc
	v_cndmask_b32_e32 v38, v38, v44, vcc
	v_cndmask_b32_e32 v37, v37, v47, vcc
	v_cndmask_b32_e32 v36, v36, v46, vcc
	v_cndmask_b32_e32 v35, v35, v41, vcc
	v_cndmask_b32_e32 v34, v34, v40, vcc
	v_cndmask_b32_e32 v33, v33, v43, vcc
	v_cndmask_b32_e32 v32, v32, v42, vcc
	v_cvt_pk_bf16_f32 v32, v32, v33
	v_cvt_pk_bf16_f32 v33, v34, v35
	v_cvt_pk_bf16_f32 v34, v36, v37
	v_cvt_pk_bf16_f32 v35, v38, v39
	ds_write_b128 v172, v[32:35] offset:37184
	s_and_saveexec_b64 s[12:13], s[10:11]
	s_cbranch_execz .LBB0_181
	v_and_b32_e32 v33, 64, v171
	v_xor_b32_e32 v32, 16, v171
	v_add_u32_e32 v33, 64, v33
	v_cmp_lt_i32_e64 s[0:1], v32, v33
	s_nop 1
	v_cndmask_b32_e64 v32, v171, v32, s[0:1]
	v_lshlrev_b32_e32 v34, 2, v32
	ds_bpermute_b32 v42, v34, v24
	ds_bpermute_b32 v32, v34, v28
	ds_bpermute_b32 v43, v34, v25
	ds_bpermute_b32 v33, v34, v29
	ds_bpermute_b32 v54, v34, v26
	ds_bpermute_b32 v52, v34, v30
	ds_bpermute_b32 v55, v34, v27
	ds_bpermute_b32 v53, v34, v31
	v_add_lshl_u32 v34, s4, v144, 6
	v_readlane_b32 s0, v245, 47
	v_and_b32_e32 v44, 0x3fbc0, v34
	v_readlane_b32 s1, v245, 48
	s_nop 4
	v_mov_b32_e32 v38, v212
	v_mov_b32_e32 v39, v213
	v_mov_b32_e32 v40, v214
	v_mov_b32_e32 v41, v215
	v_mov_b32_e32 v48, v216
	v_mov_b32_e32 v49, v217
	v_mov_b32_e32 v50, v218
	v_mov_b32_e32 v51, v219
	v_mov_b32_e32 v34, v220
	v_mov_b32_e32 v35, v221
	v_mov_b32_e32 v36, v222
	v_mov_b32_e32 v37, v223
	s_nop 0
	v_mov_b32_e32 v44, v224
	v_mov_b32_e32 v45, v225
	v_mov_b32_e32 v46, v226
	v_mov_b32_e32 v47, v227
	v_cmp_lt_i32_e64 s[0:1], 0, v133
	s_and_saveexec_b64 s[14:15], s[0:1]
	s_xor_b64 s[14:15], exec, s[14:15]
	s_cbranch_execz .LBB0_178
	v_cmp_eq_u32_e64 s[0:1], 1, v133
	s_and_saveexec_b64 s[16:17], s[0:1]
	s_cbranch_execz .LBB0_177
	s_waitcnt vmcnt(8) lgkmcnt(1)
	v_pk_mul_f32 v[50:51], v[50:51], v[54:55]
	v_pk_mul_f32 v[42:43], v[48:49], v[42:43]
	s_waitcnt lgkmcnt(0)
	v_pk_mul_f32 v[40:41], v[40:41], v[52:53]
	v_pk_mul_f32 v[32:33], v[38:39], v[32:33]
	s_waitcnt vmcnt(8)
	v_pk_fma_f32 v[26:27], v[26:27], v[46:47], v[50:51]
	v_pk_fma_f32 v[24:25], v[24:25], v[44:45], v[42:43]
	v_pk_fma_f32 v[30:31], v[30:31], v[36:37], v[40:41]
	v_pk_fma_f32 v[28:29], v[28:29], v[34:35], v[32:33]

;     __device__ __forceinline__ void to_lds(f32x4 (&acc)[4][4], bf16_t* st, int row0, int col0, int wr, int wc, int fr, int fq) const {
;     ...
;                 if (pp == 0 && dorope) {
;                     f32x4 p0, p1;
; #pragma unroll
;                     for (int j = 0; j < 4; ++j) { p0[j] = __shfl_xor(v0[j], 16); p1[j] = __shfl_xor(v1[j], 16); }
;                     const float* rp = rope + s * 16;
;                     const f32x4 c0 = *(const f32x4*)rp, c1 = *(const f32x4*)(rp + 4), s0 = *(const f32x4*)(rp + 8), s1 = *(const f32x4*)(rp + 12);
;                     if (fq == 0) { v0 = v0 * c0 - p0 * s0; v1 = v1 * c1 - p1 * s1; }
;                     else if (fq == 1) { v0 = v0 * c0 + p0 * s0; v1 = v1 * c1 + p1 * s1; }
;                 }
.LBB0_178:
	s_andn2_saveexec_b64 s[0:1], s[14:15]
	s_cbranch_execz .LBB0_180
	s_waitcnt vmcnt(8) lgkmcnt(1)
	v_pk_mul_f32 v[50:51], v[50:51], v[54:55]
	v_pk_mul_f32 v[42:43], v[48:49], v[42:43]
	s_waitcnt lgkmcnt(0)
	v_pk_mul_f32 v[40:41], v[40:41], v[52:53]
	v_pk_mul_f32 v[32:33], v[38:39], v[32:33]
	s_waitcnt vmcnt(8)
	v_pk_fma_f32 v[26:27], v[26:27], v[46:47], v[50:51] neg_lo:[0,0,1] neg_hi:[0,0,1]
	v_pk_fma_f32 v[24:25], v[24:25], v[44:45], v[42:43] neg_lo:[0,0,1] neg_hi:[0,0,1]
	v_pk_fma_f32 v[30:31], v[30:31], v[36:37], v[40:41] neg_lo:[0,0,1] neg_hi:[0,0,1]
	v_pk_fma_f32 v[28:29], v[28:29], v[34:35], v[32:33] neg_lo:[0,0,1] neg_hi:[0,0,1]

; __device__ __forceinline__ u32x4 pack8(f32x4 a, f32x4 b) { u32x4 r; r.x = cvt_pk_bf16(a[0], a[1]); r.y = cvt_pk_bf16(a[2], a[3]); r.z = cvt_pk_bf16(b[0], b[1]); r.w = cvt_pk_bf16(b[2], b[3]); return r; }
;     __device__ __forceinline__ void to_lds(f32x4 (&acc)[4][4], bf16_t* st, int row0, int col0, int wr, int wc, int fr, int fq) const {
;     ...
;             for (int pp = 0; pp < 2; ++pp) {
;                 f32x4 v0 = acc[m][2 * pp], v1 = acc[m][2 * pp + 1];
;                 if (pp == 0 && dorope) {
;                     f32x4 p0, p1;
; #pragma unroll
;                     for (int j = 0; j < 4; ++j) { p0[j] = __shfl_xor(v0[j], 16); p1[j] = __shfl_xor(v1[j], 16); }
;                     const float* rp = rope + s * 16;
;                     const f32x4 c0 = *(const f32x4*)rp, c1 = *(const f32x4*)(rp + 4), s0 = *(const f32x4*)(rp + 8), s1 = *(const f32x4*)(rp + 12);
;                     if (fq == 0) { v0 = v0 * c0 - p0 * s0; v1 = v1 * c1 - p1 * s1; }
;                     else if (fq == 1) { v0 = v0 * c0 + p0 * s0; v1 = v1 * c1 + p1 * s1; }
;                 }
;                 if (isq) { v0 = v0 * 0.18033688011112042f; v1 = v1 * 0.18033688011112042f; }
;                 *(u32x4*)(st + rl * 136 + wc * 64 + pp * 32 + 8 * fq) = pack8(v0, v1);
.LBB0_181:
	s_or_b64 exec, exec, s[12:13]
	s_waitcnt lgkmcnt(4)
	v_pk_mul_f32 v[32:33], v[26:27], s[2:3] op_sel_hi:[1,0]
	s_waitcnt vmcnt(8)
	v_pk_mul_f32 v[34:35], v[24:25], s[2:3] op_sel_hi:[1,0]
	v_pk_mul_f32 v[36:37], v[30:31], s[2:3] op_sel_hi:[1,0]
	v_pk_mul_f32 v[38:39], v[28:29], s[2:3] op_sel_hi:[1,0]
	v_cndmask_b32_e32 v31, v31, v37, vcc
	v_cndmask_b32_e32 v30, v30, v36, vcc
	v_cndmask_b32_e32 v29, v29, v39, vcc
	v_cndmask_b32_e32 v28, v28, v38, vcc
	v_cndmask_b32_e32 v27, v27, v33, vcc
	v_cndmask_b32_e32 v26, v26, v32, vcc
	v_cndmask_b32_e32 v25, v25, v35, vcc
	v_cndmask_b32_e32 v24, v24, v34, vcc
	v_cvt_pk_bf16_f32 v24, v24, v25
	v_cvt_pk_bf16_f32 v25, v26, v27
	v_cvt_pk_bf16_f32 v26, v28, v29
	v_cvt_pk_bf16_f32 v27, v30, v31
	ds_write_b128 v172, v[24:27] offset:41472
	v_pk_mul_f32 v[24:25], v[18:19], s[2:3] op_sel_hi:[1,0]
	v_pk_mul_f32 v[26:27], v[16:17], s[2:3] op_sel_hi:[1,0]
	v_pk_mul_f32 v[28:29], v[22:23], s[2:3] op_sel_hi:[1,0]
	v_pk_mul_f32 v[30:31], v[20:21], s[2:3] op_sel_hi:[1,0]
	v_cndmask_b32_e32 v23, v23, v29, vcc
	v_cndmask_b32_e32 v22, v22, v28, vcc
	v_cndmask_b32_e32 v21, v21, v31, vcc
	v_cndmask_b32_e32 v20, v20, v30, vcc
	v_cndmask_b32_e32 v19, v19, v25, vcc
	v_cndmask_b32_e32 v18, v18, v24, vcc
	v_cndmask_b32_e32 v17, v17, v27, vcc
	v_cndmask_b32_e32 v16, v16, v26, vcc
	v_cvt_pk_bf16_f32 v16, v16, v17
	v_cvt_pk_bf16_f32 v17, v18, v19
	v_cvt_pk_bf16_f32 v18, v20, v21
	v_cvt_pk_bf16_f32 v19, v22, v23
	ds_write_b128 v172, v[16:19] offset:41536
	s_and_saveexec_b64 s[12:13], s[10:11]
	s_cbranch_execz .LBB0_148
	v_and_b32_e32 v17, 64, v171
	v_xor_b32_e32 v16, 16, v171
	v_add_u32_e32 v17, 64, v17
	v_cmp_lt_i32_e64 s[0:1], v16, v17
	s_nop 1
	v_cndmask_b32_e64 v16, v171, v16, s[0:1]
	v_lshlrev_b32_e32 v18, 2, v16
	ds_bpermute_b32 v26, v18, v8
	ds_bpermute_b32 v16, v18, v12
	ds_bpermute_b32 v27, v18, v9
	ds_bpermute_b32 v17, v18, v13
	ds_bpermute_b32 v38, v18, v10
	ds_bpermute_b32 v36, v18, v14
	ds_bpermute_b32 v39, v18, v11
	ds_bpermute_b32 v37, v18, v15
	v_add_lshl_u32 v18, s4, v145, 6
	v_readlane_b32 s0, v245, 47
	v_and_b32_e32 v28, 0x3ffc0, v18
	v_readlane_b32 s1, v245, 48
	s_nop 4
	v_mov_b32_e32 v22, v228
	v_mov_b32_e32 v23, v229
	v_mov_b32_e32 v24, v230
	v_mov_b32_e32 v25, v231
	v_mov_b32_e32 v32, v232
	v_mov_b32_e32 v33, v233
	v_mov_b32_e32 v34, v234
	v_mov_b32_e32 v35, v235
	v_mov_b32_e32 v18, v236
	v_mov_b32_e32 v19, v237
	v_mov_b32_e32 v20, v238
	v_mov_b32_e32 v21, v239
	s_nop 0
	v_mov_b32_e32 v28, v240
	v_mov_b32_e32 v29, v241
	v_mov_b32_e32 v30, v242
	v_mov_b32_e32 v31, v243
	v_cmp_lt_i32_e64 s[0:1], 0, v133
	s_and_saveexec_b64 s[10:11], s[0:1]
	s_xor_b64 s[10:11], exec, s[10:11]
	s_cbranch_execz .LBB0_186
	v_cmp_eq_u32_e64 s[0:1], 1, v133
	s_and_saveexec_b64 s[14:15], s[0:1]
	s_cbranch_execz .LBB0_185
	s_waitcnt vmcnt(8) lgkmcnt(1)
	v_pk_mul_f32 v[34:35], v[34:35], v[38:39]
	v_pk_mul_f32 v[26:27], v[32:33], v[26:27]
	s_waitcnt lgkmcnt(0)
	v_pk_mul_f32 v[24:25], v[24:25], v[36:37]
	v_pk_mul_f32 v[16:17], v[22:23], v[16:17]
	s_waitcnt vmcnt(8)
	v_pk_fma_f32 v[10:11], v[10:11], v[30:31], v[34:35]
	v_pk_fma_f32 v[8:9], v[8:9], v[28:29], v[26:27]
	v_pk_fma_f32 v[14:15], v[14:15], v[20:21], v[24:25]
	v_pk_fma_f32 v[12:13], v[12:13], v[18:19], v[16:17]

; template <class Epi>
; __device__ __forceinline__ void gemm_tile(const bf16_t* __restrict__ A, const bf16_t* __restrict__ Bt, int K, int row0, int col0, const Epi& epi, char* smem,
;                                           bool prefetched, bool nvalid, int nrow0, int ncol0) {
;     ...
;     int soffA[4], soffB[4];
; #pragma unroll
;     for (int i = 0; i < 4; ++i) {
;         const int row = (w + 4 * i) * 8 + (lane >> 3), cp = lane & 7;
;         soffA[i] = row * K + (cp ^ ((row >> 1) & 7)) * 8;
;         soffB[i] = row * K + (cp ^ (((row >> 1) & 1) | (((row >> 3) & 1) << 1) | (((row >> 4) & 1) << 2))) * 8;
;     }
;     const bf16_t* pA = A + (size_t)row0 * K;
;     const bf16_t* pB = Bt + (size_t)col0 * K;
;     ...
;     int offA[4][2], offB[4][2];
; #pragma unroll
;     for (int m = 0; m < 4; ++m)
; #pragma unroll
;         for (int ks = 0; ks < 2; ++ks) { const int cx = ((ks * 4 + fq) ^ ((fr >> 1) & 7)) * 16;
;             offA[m][ks] = (wr * 64 + m * 16 + fr) * 128 + cx;
;             offB[m][ks] = TILE_B + (wc * 64 + (m >> 1) * 32 + 8 * (fr >> 2) + 4 * (m & 1) + (fr & 3)) * 128 + cx; }
; template <class E1, class E2>
; __device__ __forceinline__ void gemm_phase2(const bf16_t* A1, const bf16_t* B1, int M1, int N1, const E1& e1,
;                                             const bf16_t* A2, const bf16_t* B2, int M2, int N2, const E2& e2, int K, char* smem) {
;     ...
;     const int nM2 = M2 >> 7, nt2 = nM2 * (N2 >> 7), G = gridDim.x;
;     bool pre = false;
;     for (int i = (blockIdx.x + (G >> 1)) % G; i < nt2; i += G) {
;         const int j = i + G; const bool nv = j < nt2;
;         gemm_tile(A2, B2, K, (i % nM2) << 7, (i / nM2) << 7, e2, smem, pre, nv, (j % nM2) << 7, (j / nM2) << 7);
.LBB0_186:
	s_andn2_saveexec_b64 s[0:1], s[10:11]
	s_cbranch_execz .LBB0_147
	s_waitcnt vmcnt(8) lgkmcnt(1)
	v_pk_mul_f32 v[34:35], v[34:35], v[38:39]
	v_pk_mul_f32 v[26:27], v[32:33], v[26:27]
	s_waitcnt lgkmcnt(0)
	v_pk_mul_f32 v[24:25], v[24:25], v[36:37]
	v_pk_mul_f32 v[16:17], v[22:23], v[16:17]
	s_waitcnt vmcnt(8)
	v_pk_fma_f32 v[10:11], v[10:11], v[30:31], v[34:35] neg_lo:[0,0,1] neg_hi:[0,0,1]
	v_pk_fma_f32 v[8:9], v[8:9], v[28:29], v[26:27] neg_lo:[0,0,1] neg_hi:[0,0,1]
	v_pk_fma_f32 v[14:15], v[14:15], v[20:21], v[24:25] neg_lo:[0,0,1] neg_hi:[0,0,1]
	v_pk_fma_f32 v[12:13], v[12:13], v[18:19], v[16:17] neg_lo:[0,0,1] neg_hi:[0,0,1]
	s_branch .LBB0_147
.LBB0_188:
	s_waitcnt vmcnt(8) lgkmcnt(0)
	v_readlane_b32 s21, v245, 0
	s_barrier
.LBB0_189:
	v_cvt_f32_u32_e32 v0, s58
	s_add_u32 s0, s56, 0x10000000
	v_writelane_b32 v245, s0, 57
	s_addc_u32 s0, s57, 0
	v_rcp_iflag_f32_e32 v0, v0
	s_sub_i32 s1, 0, s58
	v_writelane_b32 v245, s0, 58
	s_ashr_i32 s0, s58, 1
	v_mul_f32_e32 v0, 0x4f7ffffe, v0
	v_cvt_u32_f32_e32 v0, v0
	s_add_i32 s0, s0, s21
	v_bfe_u32 v159, v114, 6, 1
	v_lshlrev_b32_e32 v160, 6, v159
	v_readfirstlane_b32 s2, v0
	s_mul_i32 s1, s1, s2
	s_mul_hi_u32 s1, s2, s1
	s_add_i32 s2, s2, s1
	s_mul_hi_u32 s1, s0, s2
	s_mul_i32 s1, s1, s58
	s_sub_i32 s0, s0, s1
	s_sub_i32 s1, s0, s58
	s_cmp_ge_u32 s0, s58
	s_cselect_b32 s0, s1, s0
	s_sub_i32 s1, s0, s58
	s_cmp_ge_u32 s0, s58
	s_cselect_b32 s0, s1, s0
	s_cmpk_gt_i32 s0, 0x3ff
	v_and_b32_e32 v161, 3, v114
	v_writelane_b32 v245, s0, 59
	s_cbranch_scc1 .LBB0_201
	v_and_b32_e32 v2, 4, v156
	v_lshrrev_b32_e32 v0, 1, v135
	v_and_b32_e32 v1, 2, v155
	v_xor_b32_e32 v0, v0, v114
	v_and_or_b32 v2, v147, 1, v2
	v_lshlrev_b32_e32 v0, 3, v0
	v_bitop3_b32 v1, v2, v154, v1 bitop3:0x36
	v_lshlrev_b32_e32 v3, 10, v135
	v_and_b32_e32 v5, 56, v0
	v_lshlrev_b32_e32 v1, 3, v1
	v_add_u32_e32 v2, 32, v135
	v_or_b32_e32 v0, v5, v3
	v_or_b32_e32 v64, v1, v3
	v_lshlrev_b32_e32 v3, 10, v2
	v_lshrrev_b32_e32 v2, 1, v2
	v_xor_b32_e32 v2, v2, v114
	v_lshlrev_b32_e32 v2, 3, v2
	v_and_b32_e32 v7, 56, v2
	v_or_b32_e32 v2, v7, v3
	v_or_b32_e32 v66, v1, v3
	v_add_u32_e32 v3, 64, v135
	v_lshlrev_b32_e32 v6, 10, v3
	v_lshrrev_b32_e32 v3, 1, v3
	v_xor_b32_e32 v3, v3, v114
	v_lshlrev_b32_e32 v3, 3, v3
	v_and_b32_e32 v3, 56, v3
	v_or_b32_e32 v4, v3, v6
	v_or_b32_e32 v68, v1, v6
	v_add_u32_e32 v6, 0x60, v135
	v_lshlrev_b32_e32 v8, 10, v6
	v_lshrrev_b32_e32 v6, 1, v6
	v_xor_b32_e32 v6, v6, v114
	v_lshlrev_b32_e32 v6, 3, v6
	v_and_b32_e32 v9, 56, v6
	s_movk_i32 s0, 0x1c0
	v_and_b32_e32 v10, 24, v152
	v_lshl_or_b32 v16, v116, 13, v132
	v_or_b32_e32 v6, v9, v8
	v_or_b32_e32 v70, v1, v8
	v_and_or_b32 v8, v153, s0, v151
	v_bitop3_b32 v11, v133, v153, 7 bitop3:0x78
	v_or3_b32 v10, v160, v10, v161
	v_or_b32_e32 v5, v16, v5
	v_lshlrev_b32_e32 v11, 4, v11
	v_lshlrev_b32_e32 v12, 7, v8
	v_lshlrev_b32_e32 v10, 7, v10
	v_lshlrev_b32_e32 v13, 4, v134
	v_mov_b32_e32 v73, 0
	v_lshlrev_b32_e32 v72, 1, v5
	v_or_b32_e32 v5, v16, v7
	v_mov_b32_e32 v7, 0x10000
	v_or_b32_e32 v117, v11, v12
	v_or_b32_e32 v129, v10, v13
	v_or_b32_e32 v130, v10, v11
	v_lshl_add_u64 v[10:11], s[56:57], 0, v[72:73]
	s_mov_b64 s[0:1], 0x440080
	v_lshl_add_u32 v72, v5, 1, v7
	v_or_b32_e32 v3, v16, v3
	v_mov_b32_e32 v5, 0x20000
	v_lshl_add_u64 v[90:91], v[10:11], 0, s[0:1]
	v_lshl_add_u64 v[10:11], s[56:57], 0, v[72:73]
	v_lshl_add_u32 v72, v3, 1, v5
	v_or_b32_e32 v3, v16, v9
	v_mov_b32_e32 v5, 0x30000
	v_lshl_add_u64 v[92:93], v[10:11], 0, s[0:1]
	v_lshl_add_u64 v[10:11], s[56:57], 0, v[72:73]
	v_lshl_add_u32 v72, v3, 1, v5
	v_or_b32_e32 v1, v16, v1
	v_lshl_add_u64 v[94:95], v[10:11], 0, s[0:1]
	v_lshl_add_u64 v[10:11], s[56:57], 0, v[72:73]
	v_lshlrev_b32_e32 v72, 1, v1
	v_lshl_add_u64 v[96:97], v[10:11], 0, s[0:1]
	v_lshl_add_u64 v[10:11], s[56:57], 0, v[72:73]
	s_mov_b64 s[0:1], 0x3800080
	v_lshl_add_u64 v[98:99], v[10:11], 0, s[0:1]
	v_add_u32_e32 v10, 0x10000, v72
	v_mov_b32_e32 v11, v73
	v_lshl_add_u64 v[10:11], s[56:57], 0, v[10:11]
	v_lshl_add_u64 v[100:101], v[10:11], 0, s[0:1]
	v_add_u32_e32 v10, 0x20000, v72
	v_mov_b32_e32 v11, v73
	v_or_b32_e32 v128, v13, v12
	v_mul_u32_u24_e32 v13, 0x110, v8
	v_and_b32_e32 v8, 0x78, v157
	v_lshl_add_u64 v[10:11], s[56:57], 0, v[10:11]
	v_add_u32_e32 v72, 0x30000, v72
	s_add_u32 s12, s56, 0x440000
	v_lshl_or_b32 v12, v159, 7, v158
	v_lshlrev_b32_e32 v14, 1, v8
	v_mul_u32_u24_e32 v15, 0x110, v147
	v_lshlrev_b32_e32 v74, 12, v147
	v_lshl_add_u64 v[102:103], v[10:11], 0, s[0:1]
	v_lshl_add_u64 v[10:11], s[56:57], 0, v[72:73]
	s_addc_u32 s13, s57, 0
	v_mov_b32_e32 v65, v73
	v_mov_b32_e32 v67, v73
	v_mov_b32_e32 v69, v73
	v_mov_b32_e32 v71, v73
	v_mov_b32_e32 v75, v73
	v_add_u32_e32 v76, 0x10000, v74
	v_mov_b32_e32 v77, v73
	v_add_u32_e32 v78, 0x20000, v74
	v_mov_b32_e32 v79, v73
	v_add_u32_e32 v80, 0x30000, v74
	v_mov_b32_e32 v81, v73
	v_or_b32_e32 v82, 0x40000, v74
	v_mov_b32_e32 v83, v73
	v_add_u32_e32 v84, 0x50000, v74
	v_mov_b32_e32 v85, v73
	v_add_u32_e32 v86, 0x60000, v74
	v_mov_b32_e32 v87, v73
	v_add_u32_e32 v88, 0x70000, v74
	v_mov_b32_e32 v89, v73
	v_lshl_add_u64 v[104:105], v[10:11], 0, s[0:1]
	s_mov_b64 s[8:9], 0
	v_add_u32_e32 v131, 0x4000, v149
	v_add_u32_e32 v139, 0x1000, v149
	v_add_u32_e32 v140, 0x5000, v149
	v_add_u32_e32 v141, 0x2000, v149
	v_add_u32_e32 v142, 0x6000, v149
	v_add_u32_e32 v143, 0x3000, v149
	v_add_u32_e32 v144, 0x7000, v149
	v_add_u32_e32 v145, v12, v13
	v_lshlrev_b32_e32 v72, 1, v8
	v_add_u32_e32 v162, v14, v15
	v_lshlrev_b32_e32 v163, 1, v0
	v_lshlrev_b32_e32 v164, 1, v2
	v_lshlrev_b32_e32 v165, 1, v4
	v_lshlrev_b32_e32 v166, 1, v6
	v_readlane_b32 s14, v245, 59
	s_waitcnt vmcnt(8)
	s_branch .LBB0_192

; __device__ __forceinline__ f32x4 mfma16(bf16x8 a, bf16x8 b, f32x4 c) { return __builtin_amdgcn_mfma_f32_16x16x32_bf16(a, b, c, 0, 0, 0); }
; template <class Epi>
; __device__ __forceinline__ void gemm_tile(const bf16_t* __restrict__ A, const bf16_t* __restrict__ Bt, int K, int row0, int col0, const Epi& epi, char* smem,
;                                           bool prefetched, bool nvalid, int nrow0, int ncol0) {
;     ...
; #pragma unroll
;         for (int ks = 0; ks < 2; ++ks) {
;             bf16x8 a[4], b[4];
; #pragma unroll
;             for (int m = 0; m < 4; ++m) a[m] = *(const bf16x8*)(cb + offA[m][ks]);
; #pragma unroll
;             for (int n = 0; n < 4; ++n) b[n] = *(const bf16x8*)(cb + offB[n][ks]);
; #pragma unroll
;             for (int m = 0; m < 4; ++m)
; #pragma unroll
;                 for (int n = 0; n < 4; ++n) acc[m][n] = mfma16(b[n], a[m], acc[m][n]);
;         }
;         asm volatile("s_waitcnt vmcnt(0)" ::: "memory");
;         __syncthreads();
;     }
;     if (nvalid) { const bf16_t* qA = A + (size_t)nrow0 * K; const bf16_t* qB = Bt + (size_t)ncol0 * K; GLDS_STAGE(0, qA, qB, 0); }
;     __device__ __forceinline__ void to_lds(f32x4 (&acc)[4][4], bf16_t* st, int row0, int col0, int wr, int wc, int fr, int fq) const {
;     ...
;                     const float* rp = rope + s * 16;
;                     const f32x4 c0 = *(const f32x4*)rp, c1 = *(const f32x4*)(rp + 4), s0 = *(const f32x4*)(rp + 8), s1 = *(const f32x4*)(rp + 12);
.Lgk_tail_723:
	s_setprio 0
	v_mfma_f32_16x16x32_bf16 v[32:35], v[80:83], v[246:249], v[32:35]
	v_mfma_f32_16x16x32_bf16 v[36:39], v[128:131], v[246:249], v[36:39]
	v_mfma_f32_16x16x32_bf16 v[40:43], v[180:183], v[246:249], v[40:43]
	v_mfma_f32_16x16x32_bf16 v[44:47], v[184:187], v[246:249], v[44:47]
	v_mfma_f32_16x16x32_bf16 v[48:51], v[80:83], v[250:253], v[48:51]
	v_mfma_f32_16x16x32_bf16 v[52:55], v[128:131], v[250:253], v[52:55]
	v_mfma_f32_16x16x32_bf16 v[56:59], v[180:183], v[250:253], v[56:59]
	v_mfma_f32_16x16x32_bf16 v[60:63], v[184:187], v[250:253], v[60:63]
	ds_read_b128 v[64:67], v143 offset:49152
	ds_read_b128 v[68:71], v137 offset:32768
	ds_read_b128 v[72:75], v143 offset:49664
	ds_read_b128 v[76:79], v143 offset:53248
	ds_read_b128 v[80:83], v143 offset:53760
	s_add_i32 s24, s24, s58
	s_waitcnt lgkmcnt(3)
	v_mfma_f32_16x16x32_bf16 v[0:3], v[64:67], v[68:71], v[0:3]
	s_cmpk_gt_i32 s24, 0xfff
	s_cselect_b64 s[10:11], -1, 0
	s_cmpk_lt_i32 s24, 0x1000
	s_waitcnt lgkmcnt(2)
	v_mfma_f32_16x16x32_bf16 v[4:7], v[72:75], v[68:71], v[4:7]
	ds_read_b128 v[188:191], v142 offset:49152
	ds_read_b128 v[192:195], v142 offset:53760
	s_waitcnt lgkmcnt(3)
	v_mfma_f32_16x16x32_bf16 v[8:11], v[76:79], v[68:71], v[8:11]
	s_waitcnt lgkmcnt(2)
	v_mfma_f32_16x16x32_bf16 v[12:15], v[80:83], v[68:71], v[12:15]
	ds_read_b128 v[68:71], v137 offset:34816
	s_waitcnt lgkmcnt(0)
	v_mfma_f32_16x16x32_bf16 v[16:19], v[64:67], v[68:71], v[16:19]
	v_mfma_f32_16x16x32_bf16 v[20:23], v[72:75], v[68:71], v[20:23]
	v_mfma_f32_16x16x32_bf16 v[24:27], v[76:79], v[68:71], v[24:27]
	v_mfma_f32_16x16x32_bf16 v[28:31], v[80:83], v[68:71], v[28:31]
	ds_read_b128 v[68:71], v137 offset:36864
	s_waitcnt lgkmcnt(0)
	v_mfma_f32_16x16x32_bf16 v[128:131], v[64:67], v[68:71], v[32:35]
	s_nop 2
	ds_read_b128 v[32:35], v137 offset:38912
	v_mfma_f32_16x16x32_bf16 v[180:183], v[72:75], v[68:71], v[36:39]
	v_mfma_f32_16x16x32_bf16 v[184:187], v[76:79], v[68:71], v[40:43]
	v_mfma_f32_16x16x32_bf16 v[68:71], v[80:83], v[68:71], v[44:47]
	s_waitcnt lgkmcnt(0)
	v_mfma_f32_16x16x32_bf16 v[64:67], v[64:67], v[32:35], v[48:51]
	v_mfma_f32_16x16x32_bf16 v[72:75], v[72:75], v[32:35], v[52:55]
	v_mfma_f32_16x16x32_bf16 v[76:79], v[76:79], v[32:35], v[56:59]
	v_mfma_f32_16x16x32_bf16 v[80:83], v[80:83], v[32:35], v[60:63]
	ds_read_b128 v[32:35], v141 offset:32768
	s_waitcnt lgkmcnt(0)
	v_mfma_f32_16x16x32_bf16 v[56:59], v[188:191], v[32:35], v[0:3]
	s_nop 2
	ds_read_b128 v[0:3], v142 offset:49664
	s_waitcnt lgkmcnt(0)
	v_mfma_f32_16x16x32_bf16 v[60:63], v[0:3], v[32:35], v[4:7]
	s_nop 2
	ds_read_b128 v[4:7], v142 offset:53248
	s_waitcnt lgkmcnt(0)
	v_mfma_f32_16x16x32_bf16 v[48:51], v[4:7], v[32:35], v[8:11]
	s_nop 2
	ds_read_b128 v[8:11], v141 offset:34816
	v_mfma_f32_16x16x32_bf16 v[52:55], v[192:195], v[32:35], v[12:15]
	s_waitcnt lgkmcnt(0)
	v_mfma_f32_16x16x32_bf16 v[40:43], v[188:191], v[8:11], v[16:19]
	v_mfma_f32_16x16x32_bf16 v[44:47], v[0:3], v[8:11], v[20:23]
	v_mfma_f32_16x16x32_bf16 v[32:35], v[4:7], v[8:11], v[24:27]
	v_mfma_f32_16x16x32_bf16 v[36:39], v[192:195], v[8:11], v[28:31]
	ds_read_b128 v[8:11], v141 offset:36864
	s_waitcnt lgkmcnt(0)
	v_mfma_f32_16x16x32_bf16 v[20:23], v[192:195], v[8:11], v[68:71]
	s_nop 2
	ds_read_b128 v[68:71], v141 offset:38912
	s_waitcnt vmcnt(0)
	v_mfma_f32_16x16x32_bf16 v[24:27], v[188:191], v[8:11], v[128:131]
	s_waitcnt lgkmcnt(0)
	s_barrier
	v_mfma_f32_16x16x32_bf16 v[28:31], v[0:3], v[8:11], v[180:183]
	v_mfma_f32_16x16x32_bf16 v[16:19], v[4:7], v[8:11], v[184:187]
	v_mfma_f32_16x16x32_bf16 v[8:11], v[188:191], v[68:71], v[64:67]
	v_mfma_f32_16x16x32_bf16 v[12:15], v[0:3], v[68:71], v[72:75]
	v_mfma_f32_16x16x32_bf16 v[0:3], v[4:7], v[68:71], v[76:79]
	v_mfma_f32_16x16x32_bf16 v[4:7], v[192:195], v[68:71], v[80:83]
	v_readlane_b32 s100, v245, 47
	v_readlane_b32 s101, v245, 48
	v_add_lshl_u32 v255, s6, v136, 6
	v_and_b32_e32 v255, 0x3f3c0, v255
	s_nop 4
	global_load_dwordx4 v[180:183], v255, s[100:101] offset:48
	global_load_dwordx4 v[184:187], v255, s[100:101] offset:32
	global_load_dwordx4 v[188:191], v255, s[100:101] offset:16
	global_load_dwordx4 v[192:195], v255, s[100:101]
	v_add_lshl_u32 v254, s6, v144, 6
	v_and_b32_e32 v254, 0x3f7c0, v254
	global_load_dwordx4 v[196:199], v254, s[100:101] offset:48
	global_load_dwordx4 v[200:203], v254, s[100:101] offset:32
	global_load_dwordx4 v[204:207], v254, s[100:101] offset:16
	global_load_dwordx4 v[208:211], v254, s[100:101]
	v_add_lshl_u32 v255, s6, v145, 6
	v_and_b32_e32 v255, 0x3fbc0, v255
	global_load_dwordx4 v[212:215], v255, s[100:101] offset:48
	global_load_dwordx4 v[216:219], v255, s[100:101] offset:32
	global_load_dwordx4 v[220:223], v255, s[100:101] offset:16
	global_load_dwordx4 v[224:227], v255, s[100:101]
	v_add_lshl_u32 v254, s6, v162, 6
	v_and_b32_e32 v254, 0x3ffc0, v254
	global_load_dwordx4 v[228:231], v254, s[100:101] offset:48
	global_load_dwordx4 v[232:235], v254, s[100:101] offset:32
	global_load_dwordx4 v[236:239], v254, s[100:101] offset:16
	global_load_dwordx4 v[240:243], v254, s[100:101]
	s_cbranch_scc0 .Lnp_723
	s_and_b32 s12, s24, 7
	s_lshl_b32 s12, s12, 3
	s_bfe_u32 s13, s24, 0x30006
	s_or_b32 s12, s12, s13
	s_lshr_b32 s13, s24, 10
	s_lshl_b32 s13, s13, 6
	s_or_b32 s12, s12, s13
	s_lshl_b32 s12, s12, 4
	s_bfe_u32 s13, s24, 0x30003
	s_or_b32 s12, s12, s13
	s_bfe_u32 s13, s24, 0x10009
	s_lshl_b32 s13, s13, 3
	s_or_b32 s13, s12, s13
	s_ashr_i32 s0, s13, 31
	s_lshr_b32 s0, s0, 28
	s_add_i32 s1, s13, s0
	s_lshl_b32 s0, s1, 3
	s_and_b32 s1, s1, 0x1fffff0
	s_and_b32 s0, s0, 0xffffff80
	s_sub_i32 s1, s13, s1
	s_lshl_b32 s12, s1, 7
	s_ashr_i32 s1, s0, 31
	s_lshl_b64 s[0:1], s[0:1], 11
	v_readlane_b32 s7, v245, 53
	s_add_u32 s0, s7, s0
	v_readlane_b32 s7, v245, 54
	s_addc_u32 s1, s7, s1
	s_ashr_i32 s13, s12, 31
	s_lshl_b64 s[12:13], s[12:13], 11
	s_add_u32 s12, s3, s12
	v_readfirstlane_b32 s7, v149
	s_addc_u32 s13, s20, s13
	s_mov_b32 m0, s7
	v_readfirstlane_b32 s7, v163
	global_load_lds_dwordx4 v174, s[0:1]
	v_lshl_add_u64 v[64:65], v[84:85], 1, s[12:13]
	s_mov_b32 m0, s7
	v_readfirstlane_b32 s7, v164
	global_load_lds_dwordx4 v[64:65], off
	s_mov_b32 m0, s7
	v_readfirstlane_b32 s7, v165
	global_load_lds_dwordx4 v175, s[0:1]
	v_lshl_add_u64 v[64:65], v[86:87], 1, s[12:13]
	s_mov_b32 m0, s7
	v_readfirstlane_b32 s7, v166
	global_load_lds_dwordx4 v[64:65], off
	s_mov_b32 m0, s7
	v_readfirstlane_b32 s7, v170
	global_load_lds_dwordx4 v176, s[0:1]
	v_lshl_add_u64 v[64:65], v[88:89], 1, s[12:13]
	s_mov_b32 m0, s7
	v_readfirstlane_b32 s7, v171
	global_load_lds_dwordx4 v[64:65], off
	s_mov_b32 m0, s7
	v_lshl_add_u64 v[64:65], v[90:91], 1, s[12:13]
	global_load_lds_dwordx4 v177, s[0:1]
	v_readfirstlane_b32 s0, v172
	s_mov_b32 m0, s0
	s_nop 0
	global_load_lds_dwordx4 v[64:65], off
	s_branch .LBB0_726

;     __device__ __forceinline__ void to_lds(f32x4 (&acc)[4][4], bf16_t* st, int row0, int col0, int wr, int wc, int fr, int fq) const {
;     ...
;                 if (pp == 0 && dorope) {
;                     f32x4 p0, p1;
; #pragma unroll
;                     for (int j = 0; j < 4; ++j) { p0[j] = __shfl_xor(v0[j], 16); p1[j] = __shfl_xor(v1[j], 16); }
;                     const float* rp = rope + s * 16;
;                     const f32x4 c0 = *(const f32x4*)rp, c1 = *(const f32x4*)(rp + 4), s0 = *(const f32x4*)(rp + 8), s1 = *(const f32x4*)(rp + 12);
;                     if (fq == 0) { v0 = v0 * c0 - p0 * s0; v1 = v1 * c1 - p1 * s1; }
;                     else if (fq == 1) { v0 = v0 * c0 + p0 * s0; v1 = v1 * c1 + p1 * s1; }
.LBB0_726:
	v_or_b32_e32 v64, s8, v148
	s_cmpk_lt_u32 s8, 0x800
	v_cmp_gt_i32_e32 vcc, s22, v64
	s_cselect_b64 s[0:1], -1, 0
	s_or_b64 s[12:13], vcc, s[0:1]
	s_and_saveexec_b64 s[14:15], s[12:13]
	s_cbranch_execz .LBB0_734
	v_cmp_lt_i32_e64 s[0:1], v139, v138
	s_nop 1
	v_cndmask_b32_e64 v64, v117, v139, s[0:1]
	v_lshlrev_b32_e32 v66, 2, v64
	ds_bpermute_b32 v74, v66, v56
	ds_bpermute_b32 v64, v66, v60
	ds_bpermute_b32 v75, v66, v57
	ds_bpermute_b32 v65, v66, v61
	ds_bpermute_b32 v130, v66, v58
	ds_bpermute_b32 v128, v66, v62
	ds_bpermute_b32 v131, v66, v59
	ds_bpermute_b32 v129, v66, v63
	v_add_lshl_u32 v66, s6, v136, 6
	v_readlane_b32 s0, v245, 47
	v_and_b32_e32 v76, 0x3f3c0, v66
	v_readlane_b32 s1, v245, 48
	s_nop 4
	s_waitcnt vmcnt(8)
	v_mov_b32_e32 v70, v180
	v_mov_b32_e32 v71, v181
	v_mov_b32_e32 v72, v182
	v_mov_b32_e32 v73, v183
	v_mov_b32_e32 v80, v184
	v_mov_b32_e32 v81, v185
	v_mov_b32_e32 v82, v186
	v_mov_b32_e32 v83, v187
	v_mov_b32_e32 v66, v188
	v_mov_b32_e32 v67, v189
	v_mov_b32_e32 v68, v190
	v_mov_b32_e32 v69, v191
	s_nop 0
	v_mov_b32_e32 v76, v192
	v_mov_b32_e32 v77, v193
	v_mov_b32_e32 v78, v194
	v_mov_b32_e32 v79, v195
	v_cmp_lt_i32_e64 s[0:1], 0, v133
	s_and_saveexec_b64 s[16:17], s[0:1]
	s_xor_b64 s[16:17], exec, s[16:17]
	s_cbranch_execz .LBB0_731
	v_cmp_eq_u32_e64 s[0:1], 1, v133
	s_and_saveexec_b64 s[18:19], s[0:1]
	s_cbranch_execz .LBB0_730
	s_waitcnt vmcnt(8) lgkmcnt(0)
	v_pk_mul_f32 v[82:83], v[82:83], v[130:131]
	v_pk_mul_f32 v[74:75], v[80:81], v[74:75]
	v_pk_mul_f32 v[72:73], v[72:73], v[128:129]
	v_pk_mul_f32 v[64:65], v[70:71], v[64:65]
	v_pk_fma_f32 v[58:59], v[58:59], v[78:79], v[82:83]
	v_pk_fma_f32 v[56:57], v[56:57], v[76:77], v[74:75]
	v_pk_fma_f32 v[62:63], v[62:63], v[68:69], v[72:73]
	v_pk_fma_f32 v[60:61], v[60:61], v[66:67], v[64:65]

;     __device__ __forceinline__ void to_lds(f32x4 (&acc)[4][4], bf16_t* st, int row0, int col0, int wr, int wc, int fr, int fq) const {
;     ...
;                     if (fq == 0) { v0 = v0 * c0 - p0 * s0; v1 = v1 * c1 - p1 * s1; }
;                     else if (fq == 1) { v0 = v0 * c0 + p0 * s0; v1 = v1 * c1 + p1 * s1; }
.LBB0_731:
	s_andn2_saveexec_b64 s[0:1], s[16:17]
	s_cbranch_execz .LBB0_733
	s_waitcnt vmcnt(8) lgkmcnt(0)
	v_pk_mul_f32 v[82:83], v[82:83], v[130:131]
	v_pk_mul_f32 v[74:75], v[80:81], v[74:75]
	v_pk_mul_f32 v[72:73], v[72:73], v[128:129]
	v_pk_mul_f32 v[64:65], v[70:71], v[64:65]
	v_pk_fma_f32 v[58:59], v[58:59], v[78:79], v[82:83] neg_lo:[0,0,1] neg_hi:[0,0,1]
	v_pk_fma_f32 v[56:57], v[56:57], v[76:77], v[74:75] neg_lo:[0,0,1] neg_hi:[0,0,1]
	v_pk_fma_f32 v[62:63], v[62:63], v[68:69], v[72:73] neg_lo:[0,0,1] neg_hi:[0,0,1]
	v_pk_fma_f32 v[60:61], v[60:61], v[66:67], v[64:65] neg_lo:[0,0,1] neg_hi:[0,0,1]

; __device__ __forceinline__ u32x4 pack8(f32x4 a, f32x4 b) { u32x4 r; r.x = cvt_pk_bf16(a[0], a[1]); r.y = cvt_pk_bf16(a[2], a[3]); r.z = cvt_pk_bf16(b[0], b[1]); r.w = cvt_pk_bf16(b[2], b[3]); return r; }
;     __device__ __forceinline__ void to_lds(f32x4 (&acc)[4][4], bf16_t* st, int row0, int col0, int wr, int wc, int fr, int fq) const {
;     ...
;         for (int m = 0; m < 4; ++m) {
;             const int rl = wr * 64 + m * 16 + fr;
;             const int s = (row0 + rl) & (S - 1);
; #pragma unroll
;             for (int pp = 0; pp < 2; ++pp) {
;                 f32x4 v0 = acc[m][2 * pp], v1 = acc[m][2 * pp + 1];
;                 if (pp == 0 && dorope) {
;                     f32x4 p0, p1;
; #pragma unroll
;                     for (int j = 0; j < 4; ++j) { p0[j] = __shfl_xor(v0[j], 16); p1[j] = __shfl_xor(v1[j], 16); }
;                     const float* rp = rope + s * 16;
;                     const f32x4 c0 = *(const f32x4*)rp, c1 = *(const f32x4*)(rp + 4), s0 = *(const f32x4*)(rp + 8), s1 = *(const f32x4*)(rp + 12);
;                     if (fq == 0) { v0 = v0 * c0 - p0 * s0; v1 = v1 * c1 - p1 * s1; }
;                     else if (fq == 1) { v0 = v0 * c0 + p0 * s0; v1 = v1 * c1 + p1 * s1; }
;                 }
;                 if (isq) { v0 = v0 * 0.18033688011112042f; v1 = v1 * 0.18033688011112042f; }
;                 *(u32x4*)(st + rl * 136 + wc * 64 + pp * 32 + 8 * fq) = pack8(v0, v1);
.LBB0_734:
	s_or_b64 exec, exec, s[14:15]
	s_waitcnt lgkmcnt(0)
	v_pk_mul_f32 v[64:65], v[58:59], s[2:3] op_sel_hi:[1,0]
	s_waitcnt vmcnt(8)
	v_pk_mul_f32 v[66:67], v[56:57], s[2:3] op_sel_hi:[1,0]
	v_pk_mul_f32 v[68:69], v[62:63], s[2:3] op_sel_hi:[1,0]
	v_pk_mul_f32 v[70:71], v[60:61], s[2:3] op_sel_hi:[1,0]
	v_cndmask_b32_e32 v63, v63, v69, vcc
	v_cndmask_b32_e32 v62, v62, v68, vcc
	v_cndmask_b32_e32 v61, v61, v71, vcc
	v_cndmask_b32_e32 v60, v60, v70, vcc
	v_cndmask_b32_e32 v59, v59, v65, vcc
	v_cndmask_b32_e32 v58, v58, v64, vcc
	v_cndmask_b32_e32 v57, v57, v67, vcc
	v_cndmask_b32_e32 v56, v56, v66, vcc
	v_cvt_pk_bf16_f32 v56, v56, v57
	v_cvt_pk_bf16_f32 v57, v58, v59
	v_cvt_pk_bf16_f32 v58, v60, v61
	v_cvt_pk_bf16_f32 v59, v62, v63
	ds_write_b128 v178, v[56:59] offset:32768
	v_pk_mul_f32 v[56:57], v[50:51], s[2:3] op_sel_hi:[1,0]
	v_pk_mul_f32 v[58:59], v[48:49], s[2:3] op_sel_hi:[1,0]
	v_pk_mul_f32 v[60:61], v[54:55], s[2:3] op_sel_hi:[1,0]
	v_pk_mul_f32 v[62:63], v[52:53], s[2:3] op_sel_hi:[1,0]
	v_cndmask_b32_e32 v55, v55, v61, vcc
	v_cndmask_b32_e32 v54, v54, v60, vcc
	v_cndmask_b32_e32 v53, v53, v63, vcc
	v_cndmask_b32_e32 v52, v52, v62, vcc
	v_cndmask_b32_e32 v51, v51, v57, vcc
	v_cndmask_b32_e32 v50, v50, v56, vcc
	v_cndmask_b32_e32 v49, v49, v59, vcc
	v_cndmask_b32_e32 v48, v48, v58, vcc
	v_cvt_pk_bf16_f32 v48, v48, v49
	v_cvt_pk_bf16_f32 v49, v50, v51
	v_cvt_pk_bf16_f32 v50, v52, v53
	v_cvt_pk_bf16_f32 v51, v54, v55
	ds_write_b128 v178, v[48:51] offset:32832
	s_and_saveexec_b64 s[14:15], s[12:13]
	s_cbranch_execz .LBB0_742
	v_cmp_lt_i32_e64 s[0:1], v139, v138
	s_nop 1
	v_cndmask_b32_e64 v48, v117, v139, s[0:1]
	v_lshlrev_b32_e32 v50, 2, v48
	ds_bpermute_b32 v58, v50, v40
	ds_bpermute_b32 v48, v50, v44
	ds_bpermute_b32 v59, v50, v41
	ds_bpermute_b32 v49, v50, v45
	ds_bpermute_b32 v70, v50, v42
	ds_bpermute_b32 v68, v50, v46
	ds_bpermute_b32 v71, v50, v43
	ds_bpermute_b32 v69, v50, v47
	v_add_lshl_u32 v50, s6, v144, 6
	v_readlane_b32 s0, v245, 47
	v_and_b32_e32 v60, 0x3f7c0, v50
	v_readlane_b32 s1, v245, 48
	s_nop 4
	v_mov_b32_e32 v54, v196
	v_mov_b32_e32 v55, v197
	v_mov_b32_e32 v56, v198
	v_mov_b32_e32 v57, v199
	v_mov_b32_e32 v64, v200
	v_mov_b32_e32 v65, v201
	v_mov_b32_e32 v66, v202
	v_mov_b32_e32 v67, v203
	v_mov_b32_e32 v50, v204
	v_mov_b32_e32 v51, v205
	v_mov_b32_e32 v52, v206
	v_mov_b32_e32 v53, v207
	s_nop 0
	v_mov_b32_e32 v60, v208
	v_mov_b32_e32 v61, v209
	v_mov_b32_e32 v62, v210
	v_mov_b32_e32 v63, v211
	v_cmp_lt_i32_e64 s[0:1], 0, v133
	s_and_saveexec_b64 s[16:17], s[0:1]
	s_xor_b64 s[16:17], exec, s[16:17]
	s_cbranch_execz .LBB0_739
	v_cmp_eq_u32_e64 s[0:1], 1, v133
	s_and_saveexec_b64 s[18:19], s[0:1]
	s_cbranch_execz .LBB0_738
	s_waitcnt vmcnt(8) lgkmcnt(1)
	v_pk_mul_f32 v[66:67], v[66:67], v[70:71]
	v_pk_mul_f32 v[58:59], v[64:65], v[58:59]
	s_waitcnt lgkmcnt(0)
	v_pk_mul_f32 v[56:57], v[56:57], v[68:69]
	v_pk_mul_f32 v[48:49], v[54:55], v[48:49]
	s_waitcnt vmcnt(8)
	v_pk_fma_f32 v[42:43], v[42:43], v[62:63], v[66:67]
	v_pk_fma_f32 v[40:41], v[40:41], v[60:61], v[58:59]
	v_pk_fma_f32 v[46:47], v[46:47], v[52:53], v[56:57]
	v_pk_fma_f32 v[44:45], v[44:45], v[50:51], v[48:49]

;     __device__ __forceinline__ void to_lds(f32x4 (&acc)[4][4], bf16_t* st, int row0, int col0, int wr, int wc, int fr, int fq) const {
;     ...
;                     if (fq == 0) { v0 = v0 * c0 - p0 * s0; v1 = v1 * c1 - p1 * s1; }
;                     else if (fq == 1) { v0 = v0 * c0 + p0 * s0; v1 = v1 * c1 + p1 * s1; }
.LBB0_739:
	s_andn2_saveexec_b64 s[0:1], s[16:17]
	s_cbranch_execz .LBB0_741
	s_waitcnt vmcnt(8) lgkmcnt(1)
	v_pk_mul_f32 v[66:67], v[66:67], v[70:71]
	v_pk_mul_f32 v[58:59], v[64:65], v[58:59]
	s_waitcnt lgkmcnt(0)
	v_pk_mul_f32 v[56:57], v[56:57], v[68:69]
	v_pk_mul_f32 v[48:49], v[54:55], v[48:49]
	s_waitcnt vmcnt(8)
	v_pk_fma_f32 v[42:43], v[42:43], v[62:63], v[66:67] neg_lo:[0,0,1] neg_hi:[0,0,1]
	v_pk_fma_f32 v[40:41], v[40:41], v[60:61], v[58:59] neg_lo:[0,0,1] neg_hi:[0,0,1]
	v_pk_fma_f32 v[46:47], v[46:47], v[52:53], v[56:57] neg_lo:[0,0,1] neg_hi:[0,0,1]
	v_pk_fma_f32 v[44:45], v[44:45], v[50:51], v[48:49] neg_lo:[0,0,1] neg_hi:[0,0,1]

; __device__ __forceinline__ u32x4 pack8(f32x4 a, f32x4 b) { u32x4 r; r.x = cvt_pk_bf16(a[0], a[1]); r.y = cvt_pk_bf16(a[2], a[3]); r.z = cvt_pk_bf16(b[0], b[1]); r.w = cvt_pk_bf16(b[2], b[3]); return r; }
;     __device__ __forceinline__ void to_lds(f32x4 (&acc)[4][4], bf16_t* st, int row0, int col0, int wr, int wc, int fr, int fq) const {
;     ...
;         for (int m = 0; m < 4; ++m) {
;             const int rl = wr * 64 + m * 16 + fr;
;             const int s = (row0 + rl) & (S - 1);
; #pragma unroll
;             for (int pp = 0; pp < 2; ++pp) {
;                 f32x4 v0 = acc[m][2 * pp], v1 = acc[m][2 * pp + 1];
;                 if (pp == 0 && dorope) {
;                     f32x4 p0, p1;
; #pragma unroll
;                     for (int j = 0; j < 4; ++j) { p0[j] = __shfl_xor(v0[j], 16); p1[j] = __shfl_xor(v1[j], 16); }
;                     const float* rp = rope + s * 16;
;                     const f32x4 c0 = *(const f32x4*)rp, c1 = *(const f32x4*)(rp + 4), s0 = *(const f32x4*)(rp + 8), s1 = *(const f32x4*)(rp + 12);
;                     if (fq == 0) { v0 = v0 * c0 - p0 * s0; v1 = v1 * c1 - p1 * s1; }
;                     else if (fq == 1) { v0 = v0 * c0 + p0 * s0; v1 = v1 * c1 + p1 * s1; }
;                 }
;                 if (isq) { v0 = v0 * 0.18033688011112042f; v1 = v1 * 0.18033688011112042f; }
;                 *(u32x4*)(st + rl * 136 + wc * 64 + pp * 32 + 8 * fq) = pack8(v0, v1);
.LBB0_742:
	s_or_b64 exec, exec, s[14:15]
	s_waitcnt lgkmcnt(4)
	v_pk_mul_f32 v[48:49], v[42:43], s[2:3] op_sel_hi:[1,0]
	s_waitcnt vmcnt(8)
	v_pk_mul_f32 v[50:51], v[40:41], s[2:3] op_sel_hi:[1,0]
	v_pk_mul_f32 v[52:53], v[46:47], s[2:3] op_sel_hi:[1,0]
	v_pk_mul_f32 v[54:55], v[44:45], s[2:3] op_sel_hi:[1,0]
	v_cndmask_b32_e32 v47, v47, v53, vcc
	v_cndmask_b32_e32 v46, v46, v52, vcc
	v_cndmask_b32_e32 v45, v45, v55, vcc
	v_cndmask_b32_e32 v44, v44, v54, vcc
	v_cndmask_b32_e32 v43, v43, v49, vcc
	v_cndmask_b32_e32 v42, v42, v48, vcc
	v_cndmask_b32_e32 v41, v41, v51, vcc
	v_cndmask_b32_e32 v40, v40, v50, vcc
	v_cvt_pk_bf16_f32 v40, v40, v41
	v_cvt_pk_bf16_f32 v41, v42, v43
	v_cvt_pk_bf16_f32 v42, v44, v45
	v_cvt_pk_bf16_f32 v43, v46, v47
	ds_write_b128 v178, v[40:43] offset:37120
	v_pk_mul_f32 v[40:41], v[34:35], s[2:3] op_sel_hi:[1,0]
	v_pk_mul_f32 v[42:43], v[32:33], s[2:3] op_sel_hi:[1,0]
	v_pk_mul_f32 v[44:45], v[38:39], s[2:3] op_sel_hi:[1,0]
	v_pk_mul_f32 v[46:47], v[36:37], s[2:3] op_sel_hi:[1,0]
	v_cndmask_b32_e32 v39, v39, v45, vcc
	v_cndmask_b32_e32 v38, v38, v44, vcc
	v_cndmask_b32_e32 v37, v37, v47, vcc
	v_cndmask_b32_e32 v36, v36, v46, vcc
	v_cndmask_b32_e32 v35, v35, v41, vcc
	v_cndmask_b32_e32 v34, v34, v40, vcc
	v_cndmask_b32_e32 v33, v33, v43, vcc
	v_cndmask_b32_e32 v32, v32, v42, vcc
	v_cvt_pk_bf16_f32 v32, v32, v33
	v_cvt_pk_bf16_f32 v33, v34, v35
	v_cvt_pk_bf16_f32 v34, v36, v37
	v_cvt_pk_bf16_f32 v35, v38, v39
	ds_write_b128 v178, v[32:35] offset:37184
	s_and_saveexec_b64 s[14:15], s[12:13]
	s_cbranch_execz .LBB0_750
	v_cmp_lt_i32_e64 s[0:1], v139, v138
	s_nop 1
	v_cndmask_b32_e64 v32, v117, v139, s[0:1]
	v_lshlrev_b32_e32 v34, 2, v32
	ds_bpermute_b32 v42, v34, v24
	ds_bpermute_b32 v32, v34, v28
	ds_bpermute_b32 v43, v34, v25
	ds_bpermute_b32 v33, v34, v29
	ds_bpermute_b32 v54, v34, v26
	ds_bpermute_b32 v52, v34, v30
	ds_bpermute_b32 v55, v34, v27
	ds_bpermute_b32 v53, v34, v31
	v_add_lshl_u32 v34, s6, v145, 6
	v_readlane_b32 s0, v245, 47
	v_and_b32_e32 v44, 0x3fbc0, v34
	v_readlane_b32 s1, v245, 48
	s_nop 4
	v_mov_b32_e32 v38, v212
	v_mov_b32_e32 v39, v213
	v_mov_b32_e32 v40, v214
	v_mov_b32_e32 v41, v215
	v_mov_b32_e32 v48, v216
	v_mov_b32_e32 v49, v217
	v_mov_b32_e32 v50, v218
	v_mov_b32_e32 v51, v219
	v_mov_b32_e32 v34, v220
	v_mov_b32_e32 v35, v221
	v_mov_b32_e32 v36, v222
	v_mov_b32_e32 v37, v223
	s_nop 0
	v_mov_b32_e32 v44, v224
	v_mov_b32_e32 v45, v225
	v_mov_b32_e32 v46, v226
	v_mov_b32_e32 v47, v227
	v_cmp_lt_i32_e64 s[0:1], 0, v133
	s_and_saveexec_b64 s[16:17], s[0:1]
	s_xor_b64 s[16:17], exec, s[16:17]
	s_cbranch_execz .LBB0_747
	v_cmp_eq_u32_e64 s[0:1], 1, v133
	s_and_saveexec_b64 s[18:19], s[0:1]
	s_cbranch_execz .LBB0_746
	s_waitcnt vmcnt(8) lgkmcnt(1)
	v_pk_mul_f32 v[50:51], v[50:51], v[54:55]
	v_pk_mul_f32 v[42:43], v[48:49], v[42:43]
	s_waitcnt lgkmcnt(0)
	v_pk_mul_f32 v[40:41], v[40:41], v[52:53]
	v_pk_mul_f32 v[32:33], v[38:39], v[32:33]
	s_waitcnt vmcnt(8)
	v_pk_fma_f32 v[26:27], v[26:27], v[46:47], v[50:51]
	v_pk_fma_f32 v[24:25], v[24:25], v[44:45], v[42:43]
	v_pk_fma_f32 v[30:31], v[30:31], v[36:37], v[40:41]
	v_pk_fma_f32 v[28:29], v[28:29], v[34:35], v[32:33]

;     __device__ __forceinline__ void to_lds(f32x4 (&acc)[4][4], bf16_t* st, int row0, int col0, int wr, int wc, int fr, int fq) const {
;     ...
;                     if (fq == 0) { v0 = v0 * c0 - p0 * s0; v1 = v1 * c1 - p1 * s1; }
;                     else if (fq == 1) { v0 = v0 * c0 + p0 * s0; v1 = v1 * c1 + p1 * s1; }
.LBB0_747:
	s_andn2_saveexec_b64 s[0:1], s[16:17]
	s_cbranch_execz .LBB0_749
	s_waitcnt vmcnt(8) lgkmcnt(1)
	v_pk_mul_f32 v[50:51], v[50:51], v[54:55]
	v_pk_mul_f32 v[42:43], v[48:49], v[42:43]
	s_waitcnt lgkmcnt(0)
	v_pk_mul_f32 v[40:41], v[40:41], v[52:53]
	v_pk_mul_f32 v[32:33], v[38:39], v[32:33]
	s_waitcnt vmcnt(8)
	v_pk_fma_f32 v[26:27], v[26:27], v[46:47], v[50:51] neg_lo:[0,0,1] neg_hi:[0,0,1]
	v_pk_fma_f32 v[24:25], v[24:25], v[44:45], v[42:43] neg_lo:[0,0,1] neg_hi:[0,0,1]
	v_pk_fma_f32 v[30:31], v[30:31], v[36:37], v[40:41] neg_lo:[0,0,1] neg_hi:[0,0,1]
	v_pk_fma_f32 v[28:29], v[28:29], v[34:35], v[32:33] neg_lo:[0,0,1] neg_hi:[0,0,1]

; __device__ __forceinline__ u32x4 pack8(f32x4 a, f32x4 b) { u32x4 r; r.x = cvt_pk_bf16(a[0], a[1]); r.y = cvt_pk_bf16(a[2], a[3]); r.z = cvt_pk_bf16(b[0], b[1]); r.w = cvt_pk_bf16(b[2], b[3]); return r; }
;     __device__ __forceinline__ void to_lds(f32x4 (&acc)[4][4], bf16_t* st, int row0, int col0, int wr, int wc, int fr, int fq) const {
;     ...
;         for (int m = 0; m < 4; ++m) {
;             const int rl = wr * 64 + m * 16 + fr;
;             const int s = (row0 + rl) & (S - 1);
; #pragma unroll
;             for (int pp = 0; pp < 2; ++pp) {
;                 f32x4 v0 = acc[m][2 * pp], v1 = acc[m][2 * pp + 1];
;                 if (pp == 0 && dorope) {
;                     f32x4 p0, p1;
; #pragma unroll
;                     for (int j = 0; j < 4; ++j) { p0[j] = __shfl_xor(v0[j], 16); p1[j] = __shfl_xor(v1[j], 16); }
;                     const float* rp = rope + s * 16;
;                     const f32x4 c0 = *(const f32x4*)rp, c1 = *(const f32x4*)(rp + 4), s0 = *(const f32x4*)(rp + 8), s1 = *(const f32x4*)(rp + 12);
;                     if (fq == 0) { v0 = v0 * c0 - p0 * s0; v1 = v1 * c1 - p1 * s1; }
;                     else if (fq == 1) { v0 = v0 * c0 + p0 * s0; v1 = v1 * c1 + p1 * s1; }
;                 }
;                 if (isq) { v0 = v0 * 0.18033688011112042f; v1 = v1 * 0.18033688011112042f; }
;                 *(u32x4*)(st + rl * 136 + wc * 64 + pp * 32 + 8 * fq) = pack8(v0, v1);
.LBB0_750:
	s_or_b64 exec, exec, s[14:15]
	s_waitcnt lgkmcnt(4)
	v_pk_mul_f32 v[32:33], v[26:27], s[2:3] op_sel_hi:[1,0]
	s_waitcnt vmcnt(8)
	v_pk_mul_f32 v[34:35], v[24:25], s[2:3] op_sel_hi:[1,0]
	v_pk_mul_f32 v[36:37], v[30:31], s[2:3] op_sel_hi:[1,0]
	v_pk_mul_f32 v[38:39], v[28:29], s[2:3] op_sel_hi:[1,0]
	v_cndmask_b32_e32 v31, v31, v37, vcc
	v_cndmask_b32_e32 v30, v30, v36, vcc
	v_cndmask_b32_e32 v29, v29, v39, vcc
	v_cndmask_b32_e32 v28, v28, v38, vcc
	v_cndmask_b32_e32 v27, v27, v33, vcc
	v_cndmask_b32_e32 v26, v26, v32, vcc
	v_cndmask_b32_e32 v25, v25, v35, vcc
	v_cndmask_b32_e32 v24, v24, v34, vcc
	v_cvt_pk_bf16_f32 v24, v24, v25
	v_cvt_pk_bf16_f32 v25, v26, v27
	v_cvt_pk_bf16_f32 v26, v28, v29
	v_cvt_pk_bf16_f32 v27, v30, v31
	ds_write_b128 v178, v[24:27] offset:41472
	v_pk_mul_f32 v[24:25], v[18:19], s[2:3] op_sel_hi:[1,0]
	v_pk_mul_f32 v[26:27], v[16:17], s[2:3] op_sel_hi:[1,0]
	v_pk_mul_f32 v[28:29], v[22:23], s[2:3] op_sel_hi:[1,0]
	v_pk_mul_f32 v[30:31], v[20:21], s[2:3] op_sel_hi:[1,0]
	v_cndmask_b32_e32 v23, v23, v29, vcc
	v_cndmask_b32_e32 v22, v22, v28, vcc
	v_cndmask_b32_e32 v21, v21, v31, vcc
	v_cndmask_b32_e32 v20, v20, v30, vcc
	v_cndmask_b32_e32 v19, v19, v25, vcc
	v_cndmask_b32_e32 v18, v18, v24, vcc
	v_cndmask_b32_e32 v17, v17, v27, vcc
	v_cndmask_b32_e32 v16, v16, v26, vcc
	v_cvt_pk_bf16_f32 v16, v16, v17
	v_cvt_pk_bf16_f32 v17, v18, v19
	v_cvt_pk_bf16_f32 v18, v20, v21
	v_cvt_pk_bf16_f32 v19, v22, v23
	ds_write_b128 v178, v[16:19] offset:41536
	s_and_saveexec_b64 s[14:15], s[12:13]
	s_cbranch_execz .LBB0_717
	v_cmp_lt_i32_e64 s[0:1], v139, v138
	s_nop 1
	v_cndmask_b32_e64 v16, v117, v139, s[0:1]
	v_lshlrev_b32_e32 v18, 2, v16
	ds_bpermute_b32 v26, v18, v8
	ds_bpermute_b32 v16, v18, v12
	ds_bpermute_b32 v27, v18, v9
	ds_bpermute_b32 v17, v18, v13
	ds_bpermute_b32 v38, v18, v10
	ds_bpermute_b32 v36, v18, v14
	ds_bpermute_b32 v39, v18, v11
	ds_bpermute_b32 v37, v18, v15
	v_add_lshl_u32 v18, s6, v162, 6
	v_readlane_b32 s0, v245, 47
	v_and_b32_e32 v28, 0x3ffc0, v18
	v_readlane_b32 s1, v245, 48
	s_nop 4
	v_mov_b32_e32 v22, v228
	v_mov_b32_e32 v23, v229
	v_mov_b32_e32 v24, v230
	v_mov_b32_e32 v25, v231
	v_mov_b32_e32 v32, v232
	v_mov_b32_e32 v33, v233
	v_mov_b32_e32 v34, v234
	v_mov_b32_e32 v35, v235
	v_mov_b32_e32 v18, v236
	v_mov_b32_e32 v19, v237
	v_mov_b32_e32 v20, v238
	v_mov_b32_e32 v21, v239
	s_nop 0
	v_mov_b32_e32 v28, v240
	v_mov_b32_e32 v29, v241
	v_mov_b32_e32 v30, v242
	v_mov_b32_e32 v31, v243
	v_cmp_lt_i32_e64 s[0:1], 0, v133
	s_and_saveexec_b64 s[12:13], s[0:1]
	s_xor_b64 s[12:13], exec, s[12:13]
	s_cbranch_execz .LBB0_755
	v_cmp_eq_u32_e64 s[0:1], 1, v133
	s_and_saveexec_b64 s[16:17], s[0:1]
	s_cbranch_execz .LBB0_754
	s_waitcnt vmcnt(8) lgkmcnt(1)
	v_pk_mul_f32 v[34:35], v[34:35], v[38:39]
	v_pk_mul_f32 v[26:27], v[32:33], v[26:27]
	s_waitcnt lgkmcnt(0)
	v_pk_mul_f32 v[24:25], v[24:25], v[36:37]
	v_pk_mul_f32 v[16:17], v[22:23], v[16:17]
	s_waitcnt vmcnt(8)
	v_pk_fma_f32 v[10:11], v[10:11], v[30:31], v[34:35]
	v_pk_fma_f32 v[8:9], v[8:9], v[28:29], v[26:27]
	v_pk_fma_f32 v[14:15], v[14:15], v[20:21], v[24:25]
	v_pk_fma_f32 v[12:13], v[12:13], v[18:19], v[16:17]

; template <class Epi>
; __device__ __forceinline__ void gemm_tile(const bf16_t* __restrict__ A, const bf16_t* __restrict__ Bt, int K, int row0, int col0, const Epi& epi, char* smem,
;                                           bool prefetched, bool nvalid, int nrow0, int ncol0) {
;     ...
;     int soffA[4], soffB[4];
; #pragma unroll
;     for (int i = 0; i < 4; ++i) {
;         const int row = (w + 4 * i) * 8 + (lane >> 3), cp = lane & 7;
;         soffA[i] = row * K + (cp ^ ((row >> 1) & 7)) * 8;
;         soffB[i] = row * K + (cp ^ (((row >> 1) & 1) | (((row >> 3) & 1) << 1) | (((row >> 4) & 1) << 2))) * 8;
;     }
;     const bf16_t* pA = A + (size_t)row0 * K;
;     const bf16_t* pB = Bt + (size_t)col0 * K;
;     ...
;     int offA[4][2], offB[4][2];
; #pragma unroll
;     for (int m = 0; m < 4; ++m)
; #pragma unroll
;         for (int ks = 0; ks < 2; ++ks) { const int cx = ((ks * 4 + fq) ^ ((fr >> 1) & 7)) * 16;
;             offA[m][ks] = (wr * 64 + m * 16 + fr) * 128 + cx;
;             offB[m][ks] = TILE_B + (wc * 64 + (m >> 1) * 32 + 8 * (fr >> 2) + 4 * (m & 1) + (fr & 3)) * 128 + cx; }
; template <class E1, class E2>
; __device__ __forceinline__ void gemm_phase2(const bf16_t* A1, const bf16_t* B1, int M1, int N1, const E1& e1,
;                                             const bf16_t* A2, const bf16_t* B2, int M2, int N2, const E2& e2, int K, char* smem) {
;     ...
;     const int nM2 = M2 >> 7, nt2 = nM2 * (N2 >> 7), G = gridDim.x;
;     bool pre = false;
;     for (int i = (blockIdx.x + (G >> 1)) % G; i < nt2; i += G) {
;         const int j = i + G; const bool nv = j < nt2;
;         gemm_tile(A2, B2, K, (i % nM2) << 7, (i / nM2) << 7, e2, smem, pre, nv, (j % nM2) << 7, (j / nM2) << 7);
.LBB0_755:
	s_andn2_saveexec_b64 s[0:1], s[12:13]
	s_cbranch_execz .LBB0_716
	s_waitcnt vmcnt(8) lgkmcnt(1)
	v_pk_mul_f32 v[34:35], v[34:35], v[38:39]
	v_pk_mul_f32 v[26:27], v[32:33], v[26:27]
	s_waitcnt lgkmcnt(0)
	v_pk_mul_f32 v[24:25], v[24:25], v[36:37]
	v_pk_mul_f32 v[16:17], v[22:23], v[16:17]
	s_waitcnt vmcnt(8)
	v_pk_fma_f32 v[10:11], v[10:11], v[30:31], v[34:35] neg_lo:[0,0,1] neg_hi:[0,0,1]
	v_pk_fma_f32 v[8:9], v[8:9], v[28:29], v[26:27] neg_lo:[0,0,1] neg_hi:[0,0,1]
	v_pk_fma_f32 v[14:15], v[14:15], v[20:21], v[24:25] neg_lo:[0,0,1] neg_hi:[0,0,1]
	v_pk_fma_f32 v[12:13], v[12:13], v[18:19], v[16:17] neg_lo:[0,0,1] neg_hi:[0,0,1]
	s_branch .LBB0_716
.LBB0_757:
	s_waitcnt vmcnt(8) lgkmcnt(0)
	s_barrier
.LBB0_758:
	v_readlane_b32 s0, v245, 59
	s_cmpk_gt_i32 s0, 0x7ff
	s_cbranch_scc1 .LBB0_770
	v_and_b32_e32 v2, 4, v156
	v_lshrrev_b32_e32 v0, 1, v135
	v_and_b32_e32 v1, 2, v155
	v_xor_b32_e32 v0, v0, v114
	v_and_or_b32 v2, v147, 1, v2
	v_lshlrev_b32_e32 v0, 3, v0
	v_bitop3_b32 v1, v2, v154, v1 bitop3:0x36
	v_lshlrev_b32_e32 v3, 10, v135
	v_and_b32_e32 v5, 56, v0
	v_lshlrev_b32_e32 v1, 3, v1
	v_add_u32_e32 v2, 32, v135
	v_or_b32_e32 v0, v5, v3
	v_or_b32_e32 v64, v1, v3
	v_lshlrev_b32_e32 v3, 10, v2
	v_lshrrev_b32_e32 v2, 1, v2
	v_xor_b32_e32 v2, v2, v114
	v_lshlrev_b32_e32 v2, 3, v2
	v_and_b32_e32 v7, 56, v2
	v_or_b32_e32 v2, v7, v3
	v_or_b32_e32 v66, v1, v3
	v_add_u32_e32 v3, 64, v135
	v_lshlrev_b32_e32 v6, 10, v3
	v_lshrrev_b32_e32 v3, 1, v3
	v_xor_b32_e32 v3, v3, v114
	v_lshlrev_b32_e32 v3, 3, v3
	v_and_b32_e32 v3, 56, v3
	v_or_b32_e32 v4, v3, v6
	v_or_b32_e32 v68, v1, v6
	v_add_u32_e32 v6, 0x60, v135
	v_lshlrev_b32_e32 v8, 10, v6
	v_lshrrev_b32_e32 v6, 1, v6
	v_xor_b32_e32 v6, v6, v114
	v_lshlrev_b32_e32 v6, 3, v6
	v_and_b32_e32 v9, 56, v6
	s_movk_i32 s0, 0x1c0
	v_and_b32_e32 v10, 24, v152
	v_lshl_or_b32 v16, v116, 13, v132
	v_or_b32_e32 v6, v9, v8
	v_or_b32_e32 v70, v1, v8
	v_and_or_b32 v8, v153, s0, v151
	v_bitop3_b32 v11, v133, v153, 7 bitop3:0x78
	v_or3_b32 v10, v160, v10, v161
	v_or_b32_e32 v5, v16, v5
	v_lshlrev_b32_e32 v11, 4, v11
	v_lshlrev_b32_e32 v12, 7, v8
	v_lshlrev_b32_e32 v10, 7, v10
	v_lshlrev_b32_e32 v13, 4, v134
	v_mov_b32_e32 v73, 0
	v_lshlrev_b32_e32 v72, 1, v5
	v_or_b32_e32 v5, v16, v7
	v_mov_b32_e32 v7, 0x10000
	v_or_b32_e32 v128, v11, v12
	v_or_b32_e32 v130, v10, v13
	v_or_b32_e32 v131, v10, v11
	v_lshl_add_u64 v[10:11], s[56:57], 0, v[72:73]
	s_mov_b64 s[0:1], 0xb40080
	v_lshl_add_u32 v72, v5, 1, v7
	v_or_b32_e32 v3, v16, v3
	v_mov_b32_e32 v5, 0x20000
	v_lshl_add_u64 v[90:91], v[10:11], 0, s[0:1]
	v_lshl_add_u64 v[10:11], s[56:57], 0, v[72:73]
	v_lshl_add_u32 v72, v3, 1, v5
	v_or_b32_e32 v3, v16, v9
	v_mov_b32_e32 v5, 0x30000
	v_lshl_add_u64 v[92:93], v[10:11], 0, s[0:1]
	v_lshl_add_u64 v[10:11], s[56:57], 0, v[72:73]
	v_lshl_add_u32 v72, v3, 1, v5
	v_or_b32_e32 v1, v16, v1
	v_lshl_add_u64 v[94:95], v[10:11], 0, s[0:1]
	v_lshl_add_u64 v[10:11], s[56:57], 0, v[72:73]
	v_lshlrev_b32_e32 v72, 1, v1
	v_lshl_add_u64 v[96:97], v[10:11], 0, s[0:1]
	v_lshl_add_u64 v[10:11], s[56:57], 0, v[72:73]
	s_mov_b64 s[0:1], 0x3800080
	v_lshl_add_u64 v[98:99], v[10:11], 0, s[0:1]
	v_add_u32_e32 v10, 0x10000, v72
	v_mov_b32_e32 v11, v73
	v_lshl_add_u64 v[10:11], s[56:57], 0, v[10:11]
	v_lshl_add_u64 v[100:101], v[10:11], 0, s[0:1]
	v_add_u32_e32 v10, 0x20000, v72
	v_mov_b32_e32 v11, v73
	v_or_b32_e32 v129, v13, v12
	v_mul_u32_u24_e32 v13, 0x110, v8
	v_and_b32_e32 v8, 0x78, v157
	v_lshl_add_u64 v[10:11], s[56:57], 0, v[10:11]
	v_add_u32_e32 v72, 0x30000, v72
	s_add_u32 s14, s56, 0xb40000
	v_lshl_or_b32 v12, v159, 7, v158
	v_lshlrev_b32_e32 v14, 1, v8
	v_mul_u32_u24_e32 v15, 0x110, v147
	v_lshlrev_b32_e32 v74, 12, v147
	v_lshl_add_u64 v[102:103], v[10:11], 0, s[0:1]
	v_lshl_add_u64 v[10:11], s[56:57], 0, v[72:73]
	s_addc_u32 s15, s57, 0
	v_mov_b32_e32 v65, v73
	v_mov_b32_e32 v67, v73
	v_mov_b32_e32 v69, v73
	v_mov_b32_e32 v71, v73
	v_mov_b32_e32 v75, v73
	v_add_u32_e32 v76, 0x10000, v74
	v_mov_b32_e32 v77, v73
	v_add_u32_e32 v78, 0x20000, v74
	v_mov_b32_e32 v79, v73
	v_add_u32_e32 v80, 0x30000, v74
	v_mov_b32_e32 v81, v73
	v_or_b32_e32 v82, 0x40000, v74
	v_mov_b32_e32 v83, v73
	v_add_u32_e32 v84, 0x50000, v74
	v_mov_b32_e32 v85, v73
	v_add_u32_e32 v86, 0x60000, v74
	v_mov_b32_e32 v87, v73
	v_add_u32_e32 v88, 0x70000, v74
	v_mov_b32_e32 v89, v73
	v_lshl_add_u64 v[104:105], v[10:11], 0, s[0:1]
	s_mov_b64 s[10:11], 0
	v_add_u32_e32 v132, 0x4000, v149
	v_add_u32_e32 v133, 0x1000, v149
	v_add_u32_e32 v134, 0x5000, v149
	v_add_u32_e32 v135, 0x2000, v149
	v_add_u32_e32 v136, 0x6000, v149
	v_add_u32_e32 v137, 0x3000, v149
	v_add_u32_e32 v141, 0x7000, v149
	v_add_u32_e32 v142, v12, v13
	v_lshlrev_b32_e32 v72, 1, v8
	v_add_u32_e32 v143, v14, v15
	v_lshlrev_b32_e32 v144, 1, v0
	v_lshlrev_b32_e32 v145, 1, v2
	v_lshlrev_b32_e32 v162, 1, v4
	v_lshlrev_b32_e32 v163, 1, v6
	s_waitcnt vmcnt(8)
	s_branch .LBB0_761
